# P2/P4 stream cache policy: nt hint also on attention Q fragment loads, SSD pass-1 xbc rows and SSD pass-3 streams (xbc rows, PREV, z), on top of v061
# baseline (speedup 1.0000x reference)
; #define LAS __attribute__((address_space(3)))
; __device__ __forceinline__ void attn_unit(LAS unsigned char* lds, const bf16_t* Q, const bf16_t* Kb, const bf16_t* V, const float* sinks, bf16_t* MIX, int nb, int kv, int tid, int lane, int wave) {
;     const int hq = kv * 8 + wave, h = lane >> 5, l31 = lane & 31;
;     bf16x8 Qf[4];
; #pragma unroll
;     for (int ks = 0; ks < 4; ++ks) Qf[ks] = *(const bf16x8*)(Q + (size_t)(128 * nb + l31) * 2048 + hq * 64 + 16 * ks + 8 * h);
; #pragma unroll
;     for (int j = 0; j < 4; ++j) { const int idx = tid + 512 * j, row = idx >> 3, ch = idx & 7; int tok = 128 * (nb - 1) + row; tok = tok < 0 ? 0 : tok;
;         const size_t go = (size_t)tok * 256 + kv * 64 + ch * 8;
;         *(LAS u32x4*)(lds + ATT_K + off64(row, ch)) = *(const u32x4*)(Kb + go);
;         *(LAS u32x4*)(lds + ATT_V + off64(row, ch)) = *(const u32x4*)(V + go); }
;     __syncthreads();
;     const float sink = sinks[hq];
.LBB0_499:
	s_ashr_i32 s1, s3, 2
	s_lshl_b32 s33, s1, 7
	s_add_i32 s42, s33, 0xffffff80
	v_add_u32_e32 v2, s42, v113
	v_add_u32_e32 v10, s42, v114
	v_add_u32_e32 v18, s42, v115
	v_add_u32_e32 v26, s42, v116
	s_and_b32 s5, s3, 3
	v_max_i32_e32 v2, 0, v2
	v_mov_b32_e32 v3, v99
	v_max_i32_e32 v10, 0, v10
	v_mov_b32_e32 v11, v99
	v_max_i32_e32 v18, 0, v18
	v_mov_b32_e32 v19, v99
	v_max_i32_e32 v26, 0, v26
	v_mov_b32_e32 v27, v99
	v_lshlrev_b64 v[2:3], 9, v[2:3]
	v_lshl_or_b32 v28, s5, 7, v124
	v_lshlrev_b64 v[10:11], 9, v[10:11]
	v_lshlrev_b64 v[18:19], 9, v[18:19]
	v_lshlrev_b64 v[26:27], 9, v[26:27]
	v_or_b32_e32 v2, v2, v28
	v_or_b32_e32 v10, v10, v28
	v_or_b32_e32 v18, v18, v28
	v_or_b32_e32 v26, v26, v28
	v_lshl_add_u64 v[4:5], s[90:91], 0, v[2:3]
	v_lshl_add_u64 v[6:7], s[92:93], 0, v[2:3]
	v_lshl_add_u64 v[12:13], s[90:91], 0, v[10:11]
	v_lshl_add_u64 v[14:15], s[92:93], 0, v[10:11]
	v_lshl_add_u64 v[20:21], s[90:91], 0, v[18:19]
	v_lshl_add_u64 v[22:23], s[92:93], 0, v[18:19]
	v_lshl_add_u64 v[28:29], s[90:91], 0, v[26:27]
	v_lshl_add_u64 v[30:31], s[92:93], 0, v[26:27]
	global_load_dwordx4 v[2:5], v[4:5], off
	s_nop 0
	global_load_dwordx4 v[6:9], v[6:7], off
	s_nop 0
	global_load_dwordx4 v[10:13], v[12:13], off
	s_nop 0
	global_load_dwordx4 v[14:17], v[14:15], off
	s_nop 0
	global_load_dwordx4 v[18:21], v[20:21], off
	s_nop 0
	global_load_dwordx4 v[22:25], v[22:23], off
	s_nop 0
	global_load_dwordx4 v[26:29], v[28:29], off
	s_nop 0
	global_load_dwordx4 v[30:33], v[30:31], off
	s_lshl_b32 s5, s5, 3
	v_or_b32_e32 v104, s33, v112
	s_add_i32 s42, s5, s75
	v_ashrrev_i32_e32 v105, 31, v104
	s_lshl_b32 s96, s42, 6
	v_lshlrev_b64 v[34:35], 12, v[104:105]
	s_ashr_i32 s97, s96, 31
	v_lshl_add_u64 v[34:35], s[88:89], 0, v[34:35]
	s_ashr_i32 s43, s42, 31
	v_lshl_add_u64 v[34:35], s[96:97], 1, v[34:35]
	s_lshl_b64 s[42:43], s[42:43], 2
	v_lshl_add_u64 v[34:35], v[34:35], 0, v[102:103]
	s_waitcnt lgkmcnt(0)
	s_add_u32 s42, s94, s42
	global_load_dwordx4 v[86:89], v[34:35], off nt
	global_load_dwordx4 v[82:85], v[34:35], off offset:32 nt
	global_load_dwordx4 v[90:93], v[34:35], off offset:64 nt
	global_load_dwordx4 v[94:97], v[34:35], off offset:96 nt
	s_addc_u32 s43, s95, s43
	s_cmp_gt_i32 s1, 0
	s_cselect_b64 s[80:81], -1, 0
	s_and_b64 s[44:45], s[80:81], s[8:9]
	s_and_b64 s[46:47], s[80:81], s[10:11]
	s_and_b64 s[48:49], s[80:81], s[12:13]
	s_and_b64 s[50:51], s[80:81], s[14:15]
	s_and_b64 s[52:53], s[80:81], s[16:17]
	s_and_b64 s[54:55], s[80:81], s[18:19]
	s_and_b64 s[56:57], s[80:81], s[20:21]
	s_and_b64 s[58:59], s[80:81], s[22:23]
	s_and_b64 s[60:61], s[80:81], s[24:25]
	s_and_b64 s[62:63], s[80:81], s[26:27]
	s_and_b64 s[64:65], s[80:81], s[28:29]
	s_and_b64 s[66:67], s[80:81], s[30:31]
	s_and_b64 s[68:69], s[80:81], s[34:35]
	s_and_b64 s[70:71], s[80:81], s[36:37]
	s_and_b64 s[72:73], s[80:81], s[38:39]
	s_mov_b32 s5, 0
	s_mov_b32 s33, 0
	s_waitcnt vmcnt(0)
	ds_write_b128 v125, v[2:5]
	ds_write_b128 v125, v[6:9] offset:32768
	ds_write_b128 v126, v[10:13]
	ds_write_b128 v126, v[14:17] offset:32768
	ds_write_b128 v127, v[18:21]
	ds_write_b128 v127, v[22:25] offset:32768
	ds_write_b128 v128, v[26:29]
	ds_write_b128 v128, v[30:33] offset:32768
	s_waitcnt lgkmcnt(0)
	s_barrier
	global_load_dword v130, v99, s[42:43]
	s_and_b64 s[42:43], s[80:81], s[6:7]
	s_branch .LBB0_501

; #define LAS __attribute__((address_space(3)))
; #define MFMA32(a, b, c) __builtin_amdgcn_mfma_f32_32x32x16_bf16((a), (b), (c), 0, 0, 0)
; __device__ __forceinline__ void attn_unit(LAS unsigned char* lds, const bf16_t* Q, const bf16_t* Kb, const bf16_t* V, const float* sinks, bf16_t* MIX, int nb, int kv, int tid, int lane, int wave) {
;     ...
;     for (int sb = 0; sb < 4; ++sb) {
;         const size_t qrow = (size_t)(128 * nb + 32 * sb + l31);
;         f32x16 S[5];
; #pragma unroll
;         for (int rel = 0; rel < 5; ++rel) {
; #pragma unroll
;             for (int e = 0; e < 16; ++e) S[rel][e] = 0.f;
; #pragma unroll
;             for (int ks = 0; ks < 4; ++ks) { const bf16x8 Kf = *(LAS const bf16x8*)(kt_ + off64(32 * (sb + rel) + l31, 2 * ks + h)); S[rel] = MFMA32(Kf, Qf[ks], S[rel]); }
;         }
;         if (sb < 3) {
; #pragma unroll
;             for (int ks = 0; ks < 4; ++ks) Qf[ks] = *(const bf16x8*)(Q + (qrow + 32) * 2048 + hq * 64 + 16 * ks + 8 * h); }
.LBB0_501:
	v_add_u32_e32 v30, s5, v123
	ds_read_b128 v[2:5], v30
	ds_read_b128 v[18:21], v30 offset:4096
	v_add_u32_e32 v46, s5, v122
	ds_read_b128 v[22:25], v46
	v_add_u32_e32 v38, s5, v121
	ds_read_b128 v[34:37], v30 offset:16384
	ds_read_b128 v[26:29], v38 offset:4096
	v_add_u32_e32 v47, s5, v120
	v_ashrrev_i32_e32 v105, 31, v104
	s_waitcnt lgkmcnt(4)
	v_mfma_f32_32x32x16_bf16 v[2:17], v[2:5], v[86:89], 0
	s_cmpk_eq_i32 s5, 0x3000
	s_waitcnt lgkmcnt(2)
	v_mfma_f32_32x32x16_bf16 v[2:17], v[22:25], v[82:85], v[2:17]
	ds_read_b128 v[22:25], v38
	v_mfma_f32_32x32x16_bf16 v[66:81], v[18:21], v[86:89], 0
	s_waitcnt lgkmcnt(0)
	v_mfma_f32_32x32x16_bf16 v[2:17], v[22:25], v[90:93], v[2:17]
	ds_read_b128 v[22:25], v47
	ds_read_b128 v[132:135], v38 offset:16384
	s_waitcnt lgkmcnt(1)
	v_mfma_f32_32x32x16_bf16 v[2:17], v[22:25], v[94:97], v[2:17]
	ds_read_b128 v[18:21], v46 offset:4096
	ds_read_b128 v[22:25], v46 offset:8192
	s_waitcnt lgkmcnt(1)
	v_mfma_f32_32x32x16_bf16 v[66:81], v[18:21], v[82:85], v[66:81]
	v_mfma_f32_32x32x16_bf16 v[66:81], v[26:29], v[90:93], v[66:81]
	ds_read_b128 v[18:21], v47 offset:4096
	ds_read_b128 v[26:29], v47 offset:8192
	s_waitcnt lgkmcnt(1)
	v_mfma_f32_32x32x16_bf16 v[66:81], v[18:21], v[94:97], v[66:81]
	ds_read_b128 v[18:21], v30 offset:8192
	ds_read_b128 v[30:33], v30 offset:12288
	s_waitcnt lgkmcnt(1)
	v_mfma_f32_32x32x16_bf16 v[50:65], v[18:21], v[86:89], 0
	ds_read_b128 v[18:21], v38 offset:8192
	ds_read_b128 v[38:41], v38 offset:12288
	ds_read_b128 v[42:45], v46 offset:12288
	ds_read_b128 v[136:139], v46 offset:16384
	v_mfma_f32_32x32x16_bf16 v[50:65], v[22:25], v[82:85], v[50:65]
	s_waitcnt lgkmcnt(3)
	v_mfma_f32_32x32x16_bf16 v[50:65], v[18:21], v[90:93], v[50:65]
	v_mfma_f32_32x32x16_bf16 v[50:65], v[26:29], v[94:97], v[50:65]
	v_mfma_f32_32x32x16_bf16 v[18:33], v[30:33], v[86:89], 0
	s_waitcnt lgkmcnt(1)
	v_mfma_f32_32x32x16_bf16 v[18:33], v[42:45], v[82:85], v[18:33]
	v_mfma_f32_32x32x16_bf16 v[18:33], v[38:41], v[90:93], v[18:33]
	ds_read_b128 v[38:41], v47 offset:12288
	ds_read_b128 v[140:143], v47 offset:16384
	s_waitcnt lgkmcnt(1)
	v_mfma_f32_32x32x16_bf16 v[18:33], v[38:41], v[94:97], v[18:33]
	v_mfma_f32_32x32x16_bf16 v[34:49], v[34:37], v[86:89], 0
	v_mfma_f32_32x32x16_bf16 v[34:49], v[136:139], v[82:85], v[34:49]
	v_mfma_f32_32x32x16_bf16 v[34:49], v[132:135], v[90:93], v[34:49]
	s_waitcnt lgkmcnt(0)
	v_mfma_f32_32x32x16_bf16 v[34:49], v[140:143], v[94:97], v[34:49]
	s_cbranch_scc1 .LBB0_500
	v_lshlrev_b64 v[82:83], 12, v[104:105]
	v_lshl_add_u64 v[82:83], s[88:89], 0, v[82:83]
	v_lshl_add_u64 v[82:83], s[96:97], 1, v[82:83]
	v_mov_b32_e32 v101, v99
	v_lshl_add_u64 v[82:83], v[82:83], 0, v[100:101]
	s_mov_b64 vcc, 0x20000
	v_lshl_add_u64 v[94:95], v[82:83], 0, vcc
	v_add_co_u32_e32 v86, vcc, 0x20000, v82
	s_nop 1
	v_addc_co_u32_e32 v87, vcc, 0, v83, vcc
	global_load_dwordx4 v[82:85], v[94:95], off offset:32 nt
	global_load_dwordx4 v[90:93], v[94:95], off offset:64 nt
	s_nop 0
	global_load_dwordx4 v[86:89], v[86:87], off nt
	s_nop 0
	global_load_dwordx4 v[94:97], v[94:95], off offset:96 nt
	s_branch .LBB0_500

; #define LAS __attribute__((address_space(3)))
; template <bool NEED_C>
; __device__ __forceinline__ void ssd_stage(LAS unsigned char* lds, const bf16_t* XBC, const float* cw, const float* cb, const float* DT, const float* a_log, int c, int g, int tid, int lane, int wave) {
;     ...
;         const int cgi = tid & 63, seg = tid >> 6;
;         int col, tch; LAS unsigned char* tile;
;         if (cgi < 32) { col = g * 256 + cgi * 8; tile = lds + SSD_XT + (cgi >> 4) * 32768; tch = cgi & 15; }
;         else if (cgi < 48) { col = 2048 + g * 128 + (cgi - 32) * 8; tile = lds + SSD_BT; tch = cgi - 32; }
;         else { col = 3072 + g * 128 + (cgi - 48) * 8; tile = lds + SSD_CT; tch = cgi - 48; }
;         if (NEED_C || cgi < 48) {
;             float w[4][8], b[8], xw[3][8];
; #pragma unroll
;             for (int k = 0; k < 4; ++k) { const f32x4 w0 = *(const f32x4*)(cw + k * XBCC + col), w1 = *(const f32x4*)(cw + k * XBCC + col + 4);
; #pragma unroll
;                 for (int e = 0; e < 4; ++e) { w[k][e] = w0[e]; w[k][4 + e] = w1[e]; } }
;             { const f32x4 b0 = *(const f32x4*)(cb + col), b1 = *(const f32x4*)(cb + col + 4);
; #pragma unroll
;               for (int e = 0; e < 4; ++e) { b[e] = b0[e]; b[4 + e] = b1[e]; } }
;             const int t0 = c * 128 + seg * 16;
;             u32x4 raw[19];
; #pragma unroll
;             for (int k = 0; k < 19; ++k) { const int tt = t0 - 3 + k;
;                 if (k >= 3 || tt >= 0) raw[k] = *(const u32x4*)(XBC + (size_t)tt * XBCC + col);
;                 else raw[k] = (u32x4){0u, 0u, 0u, 0u}; }
.LBB0_512:
	s_andn2_saveexec_b64 s[24:25], s[24:25]
	v_lshl_or_b32 v26, s89, 8, v1
	v_mov_b32_e32 v234, v168
	v_mov_b32_e32 v235, v169
	s_or_b64 exec, exec, s[24:25]
	s_ashr_i32 s88, s87, 3
	s_and_saveexec_b64 s[4:5], s[40:41]
	s_xor_b64 s[24:25], exec, s[4:5]
	s_lshl_b32 s1, s88, 7
	s_or_saveexec_b64 s[50:51], s[24:25]
	v_mov_b32_e32 v2, s1
	s_xor_b64 exec, exec, s[50:51]
	s_cbranch_execz .LBB0_524
	v_mov_b32_e32 v27, v119
	v_lshlrev_b64 v[10:11], 2, v[26:27]
	s_waitcnt lgkmcnt(0)
	v_lshl_add_u64 v[6:7], s[28:29], 0, v[10:11]
	v_add_co_u32_e32 v4, vcc, 0x4000, v6
	v_lshl_add_u64 v[2:3], v[6:7], 0, s[44:45]
	s_nop 0
	v_addc_co_u32_e32 v5, vcc, 0, v7, vcc
	v_add_co_u32_e32 v12, vcc, 0x8000, v6
	v_lshl_add_u64 v[8:9], v[6:7], 0, s[46:47]
	s_nop 0
	v_addc_co_u32_e32 v13, vcc, 0, v7, vcc
	global_load_dwordx4 v[86:89], v[6:7], off offset:16
	global_load_dwordx4 v[106:109], v[6:7], off
	global_load_dwordx4 v[14:17], v[4:5], off
	s_nop 0
	global_load_dwordx4 v[2:5], v[2:3], off offset:16
	s_nop 0
	global_load_dwordx4 v[110:113], v[12:13], off
	global_load_dwordx4 v[90:93], v[8:9], off offset:16
	v_lshl_add_u64 v[8:9], v[6:7], 0, s[48:49]
	v_add_co_u32_e32 v6, vcc, 0xc000, v6
	v_lshl_add_u64 v[22:23], s[30:31], 0, v[10:11]
	s_nop 0
	v_addc_co_u32_e32 v7, vcc, 0, v7, vcc
	global_load_dwordx4 v[18:21], v[6:7], off
	s_nop 0
	global_load_dwordx4 v[6:9], v[8:9], off offset:16
	s_nop 0
	global_load_dwordx4 v[10:13], v[22:23], off offset:16
	s_nop 0
	global_load_dwordx4 v[22:25], v[22:23], off
	s_lshl_b32 s90, s88, 7
	v_add_u32_e32 v28, s90, v172
	v_lshl_add_u64 v[26:27], v[26:27], 1, s[26:27]
	v_cmp_lt_i32_e32 vcc, -1, v28
	v_mov_b32_e32 v98, 0
	v_mov_b32_e32 v94, 0
	v_mov_b32_e32 v95, 0
	v_mov_b32_e32 v96, 0
	v_mov_b32_e32 v97, 0
	s_and_saveexec_b64 s[24:25], vcc
	s_cbranch_execz .LBB0_519
	v_mov_b32_e32 v29, v119
	v_lshlrev_b64 v[30:31], 13, v[28:29]
	v_lshl_add_u64 v[30:31], v[26:27], 0, v[30:31]
	global_load_dwordx4 v[94:97], v[30:31], off nt
.LBB0_519:
	s_or_b64 exec, exec, s[24:25]
	v_cmp_lt_i32_e64 s[24:25], -2, v28
	v_mov_b32_e32 v99, 0
	v_mov_b32_e32 v100, 0
	v_mov_b32_e32 v101, 0
	s_and_saveexec_b64 s[52:53], s[24:25]
	s_cbranch_execz .LBB0_521
	v_add_u32_e32 v30, 1, v28
	v_mov_b32_e32 v31, v119
	v_lshlrev_b64 v[30:31], 13, v[30:31]
	v_lshl_add_u64 v[30:31], v[26:27], 0, v[30:31]
	global_load_dwordx4 v[98:101], v[30:31], off nt
.LBB0_521:
	s_or_b64 exec, exec, s[52:53]
	v_mov_b32_e32 v102, 0
	v_mov_b32_e32 v103, 0
	v_mov_b32_e32 v104, 0
	v_mov_b32_e32 v105, 0
	s_and_saveexec_b64 s[24:25], vcc
	s_cbranch_execz .LBB0_523
	v_or_b32_e32 v30, 2, v28
	v_mov_b32_e32 v31, v119
	v_lshlrev_b64 v[30:31], 13, v[30:31]
	v_lshl_add_u64 v[30:31], v[26:27], 0, v[30:31]
	global_load_dwordx4 v[102:105], v[30:31], off nt
.LBB0_523:
	s_or_b64 exec, exec, s[24:25]
	v_add_u32_e32 v30, s90, v171
	v_ashrrev_i32_e32 v31, 31, v30
	v_ashrrev_i32_e32 v29, 31, v28
	v_lshlrev_b64 v[30:31], 13, v[30:31]
	v_lshlrev_b64 v[28:29], 13, v[28:29]
	v_lshl_add_u64 v[30:31], v[26:27], 0, v[30:31]
	v_lshl_add_u64 v[26:27], v[26:27], 0, v[28:29]
	v_add_co_u32_e32 v28, vcc, s3, v26
	s_waitcnt vmcnt(0)
	v_lshlrev_b32_e32 v241, 16, v98
	v_addc_co_u32_e32 v29, vcc, 0, v27, vcc
	global_load_dwordx4 v[114:117], v[30:31], off nt
	global_load_dwordx4 v[78:81], v[28:29], off nt
	v_lshlrev_b32_e32 v240, 16, v94
	v_mov_b32_e32 v150, v106
	v_mov_b32_e32 v151, v14
	v_pk_mul_f32 v[34:35], v[150:151], v[240:241]
	v_lshlrev_b32_e32 v162, 16, v102
	v_add_f32_e32 v14, v22, v34
	v_mov_b32_e32 v152, v110
	v_mov_b32_e32 v153, v18
	v_add_f32_e32 v14, v14, v35
	v_and_b32_e32 v243, 0xffff0000, v98
	v_and_b32_e32 v242, 0xffff0000, v94
	v_and_b32_e32 v160, 0xffff0000, v102
	v_lshlrev_b32_e32 v244, 16, v95
	v_lshlrev_b32_e32 v245, 16, v99
	v_lshlrev_b32_e32 v156, 16, v103
	v_and_b32_e32 v247, 0xffff0000, v99
	v_and_b32_e32 v246, 0xffff0000, v95
	v_add_co_u32_e32 v28, vcc, s66, v26
	v_and_b32_e32 v249, 0xffff0000, v100
	s_nop 0
	v_addc_co_u32_e32 v29, vcc, 0, v27, vcc
	v_add_co_u32_e32 v30, vcc, s65, v26
	v_and_b32_e32 v248, 0xffff0000, v96
	s_nop 0
	v_addc_co_u32_e32 v31, vcc, 0, v27, vcc
	global_load_dwordx4 v[82:85], v[28:29], off nt
	global_load_dwordx4 v[70:73], v[30:31], off nt
	v_lshlrev_b32_e32 v250, 16, v97
	v_lshlrev_b32_e32 v251, 16, v101
	v_add_co_u32_e32 v28, vcc, s67, v26
	v_and_b32_e32 v101, 0xffff0000, v101
	s_nop 0
	v_addc_co_u32_e32 v29, vcc, 0, v27, vcc
	v_add_co_u32_e32 v30, vcc, s61, v26
	s_waitcnt vmcnt(3)
; __device__ __forceinline__ unsigned cvt_pk_bf16(float lo, float hi) { unsigned r; asm volatile("v_cvt_pk_bf16_f32 %0, %1, %2" : "=v"(r) : "v"(lo), "v"(hi)); return r; }
; #define LAS __attribute__((address_space(3)))
; __device__ __forceinline__ float silu_f(float x) { return x * __builtin_amdgcn_rcpf(1.f + __expf(-x)); }
; template <bool NEED_C>
; __device__ __forceinline__ void ssd_stage(LAS unsigned char* lds, const bf16_t* XBC, const float* cw, const float* cb, const float* DT, const float* a_log, int c, int g, int tid, int lane, int wave) {
;     ...
;             u32x4 raw[19];
; #pragma unroll
;             for (int k = 0; k < 19; ++k) { const int tt = t0 - 3 + k;
;                 if (k >= 3 || tt >= 0) raw[k] = *(const u32x4*)(XBC + (size_t)tt * XBCC + col);
;                 else raw[k] = (u32x4){0u, 0u, 0u, 0u}; }
;             asm volatile("" ::: "memory");
; #pragma unroll
;             for (int k = 0; k < 3; ++k) unpack8(raw[k], xw[k]);
; #pragma unroll
;             for (int i = 0; i < 16; ++i) { float xv[8]; unpack8(raw[3 + i], xv);
;                 float o[8];
; #pragma unroll
;                 for (int e = 0; e < 8; ++e) { o[e] = silu_f(b[e] + w[0][e] * xw[0][e] + w[1][e] * xw[1][e] + w[2][e] * xw[2][e] + w[3][e] * xv[e]); xw[0][e] = xw[1][e]; xw[1][e] = xw[2][e]; xw[2][e] = xv[e]; }
;                 u32x4 pk; pk.x = cvt_pk_bf16(o[0], o[1]); pk.y = cvt_pk_bf16(o[2], o[3]); pk.z = cvt_pk_bf16(o[4], o[5]); pk.w = cvt_pk_bf16(o[6], o[7]);
;                 *(LAS u32x4*)(tile + off_b(seg * 16 + i, tch)) = pk; }
	v_lshlrev_b32_e32 v163, 16, v114
	v_pk_mul_f32 v[34:35], v[152:153], v[162:163]
	v_and_b32_e32 v161, 0xffff0000, v114
	v_add_f32_e32 v14, v14, v34
	v_add_f32_e32 v158, v14, v35
	v_mul_f32_e32 v14, 0xbfb8aa3b, v158
	v_exp_f32_e32 v14, v14
	v_lshlrev_b32_e32 v157, 16, v115
	v_addc_co_u32_e32 v31, vcc, 0, v27, vcc
	v_add_f32_e32 v159, 1.0, v14
	v_mov_b32_e32 v14, v107
	v_pk_mul_f32 v[106:107], v[14:15], v[242:243]
	global_load_dwordx4 v[74:77], v[28:29], off nt
	global_load_dwordx4 v[62:65], v[30:31], off nt
	v_add_f32_e32 v18, v23, v106
	v_add_f32_e32 v94, v18, v107
	v_mov_b32_e32 v18, v111
	v_pk_mul_f32 v[106:107], v[18:19], v[160:161]
	v_add_co_u32_e32 v28, vcc, s68, v26
	v_add_f32_e32 v94, v94, v106
	v_add_f32_e32 v98, v94, v107
	v_mov_b32_e32 v106, v108
	v_mov_b32_e32 v107, v16
	v_pk_mul_f32 v[110:111], v[106:107], v[244:245]
	v_mul_f32_e32 v94, 0xbfb8aa3b, v98
	v_add_f32_e32 v16, v24, v110
	v_add_f32_e32 v16, v16, v111
	v_mov_b32_e32 v110, v112
	v_mov_b32_e32 v111, v20
	v_pk_mul_f32 v[154:155], v[110:111], v[156:157]
	v_exp_f32_e32 v94, v94
	v_add_f32_e32 v16, v16, v154
	v_add_f32_e32 v102, v16, v155
	v_mul_f32_e32 v16, 0xbfb8aa3b, v102
	v_exp_f32_e32 v16, v16
	v_add_f32_e32 v20, 1.0, v94
	v_rcp_f32_e32 v112, v20
	v_and_b32_e32 v155, 0xffff0000, v115
	v_add_f32_e32 v16, 1.0, v16
	v_rcp_f32_e32 v114, v16
	v_mov_b32_e32 v16, v109
	v_pk_mul_f32 v[94:95], v[16:17], v[246:247]
	v_and_b32_e32 v154, 0xffff0000, v103
	v_add_f32_e32 v20, v25, v94
	v_add_f32_e32 v99, v20, v95
	v_mov_b32_e32 v20, v113
	v_pk_mul_f32 v[94:95], v[20:21], v[154:155]
	v_rcp_f32_e32 v108, v159
	v_add_f32_e32 v94, v99, v94
	v_add_f32_e32 v113, v94, v95
	v_mul_f32_e32 v94, 0xbfb8aa3b, v113
	v_exp_f32_e32 v94, v94
	v_mul_f32_e32 v236, v158, v108
	v_mul_f32_e32 v237, v98, v112
	v_lshlrev_b32_e32 v109, 16, v100
	v_add_f32_e32 v94, 1.0, v94
	v_rcp_f32_e32 v112, v94
	v_lshlrev_b32_e32 v108, 16, v96
	v_mov_b32_e32 v94, v86
	v_mov_b32_e32 v95, v2
	v_pk_mul_f32 v[98:99], v[94:95], v[108:109]
	v_lshlrev_b32_e32 v159, 16, v116
	v_add_f32_e32 v2, v10, v98
	v_add_f32_e32 v2, v2, v99
	v_lshlrev_b32_e32 v158, 16, v104
	v_mov_b32_e32 v98, v90
	v_mov_b32_e32 v99, v6
	v_mul_f32_e32 v238, v102, v114
	v_pk_mul_f32 v[102:103], v[98:99], v[158:159]
	v_and_b32_e32 v115, 0xffff0000, v116
	v_add_f32_e32 v2, v2, v102
	v_add_f32_e32 v108, v2, v103
	v_mul_f32_e32 v2, 0xbfb8aa3b, v108
	v_exp_f32_e32 v90, v2
	v_mov_b32_e32 v2, v87
	v_pk_mul_f32 v[86:87], v[2:3], v[248:249]
	v_and_b32_e32 v114, 0xffff0000, v104
	v_add_f32_e32 v6, v11, v86
	v_add_f32_e32 v96, v6, v87
	v_mov_b32_e32 v6, v91
	v_pk_mul_f32 v[86:87], v[6:7], v[114:115]
	v_lshlrev_b32_e32 v102, 16, v105
	v_add_f32_e32 v86, v96, v86
	v_add_f32_e32 v96, v86, v87
	v_mul_f32_e32 v86, 0xbfb8aa3b, v96
	v_exp_f32_e32 v86, v86
	v_add_f32_e32 v87, 1.0, v90
	v_rcp_f32_e32 v116, v87
	v_mov_b32_e32 v87, v4
	v_add_f32_e32 v239, 1.0, v86
	v_mov_b32_e32 v86, v88
	v_pk_mul_f32 v[90:91], v[86:87], v[250:251]
	v_lshlrev_b32_e32 v103, 16, v117
	v_add_f32_e32 v4, v12, v90
	v_add_f32_e32 v4, v4, v91
	v_mov_b32_e32 v90, v92
	v_mov_b32_e32 v91, v8
	v_mul_f32_e32 v104, v113, v112
	v_pk_mul_f32 v[112:113], v[90:91], v[102:103]
	v_addc_co_u32_e32 v29, vcc, 0, v27, vcc
	v_add_f32_e32 v4, v4, v112
	v_add_f32_e32 v92, v4, v113
	v_mul_f32_e32 v4, 0xbfb8aa3b, v92
	v_add_co_u32_e32 v30, vcc, s69, v26
	v_exp_f32_e32 v240, v4
	v_and_b32_e32 v100, 0xffff0000, v97
	v_mov_b32_e32 v4, v89
	v_addc_co_u32_e32 v31, vcc, 0, v27, vcc
	v_pk_mul_f32 v[88:89], v[4:5], v[100:101]
	global_load_dwordx4 v[66:69], v[28:29], off nt
	global_load_dwordx4 v[54:57], v[30:31], off nt
	v_add_co_u32_e32 v28, vcc, s70, v26
	v_add_f32_e32 v8, v13, v88
	s_nop 0
	v_addc_co_u32_e32 v29, vcc, 0, v27, vcc
	v_add_f32_e32 v97, v8, v89
	v_and_b32_e32 v113, 0xffff0000, v117
	v_and_b32_e32 v112, 0xffff0000, v105
	v_mov_b32_e32 v8, v93
	v_add_co_u32_e32 v30, vcc, s63, v26
	v_pk_mul_f32 v[88:89], v[8:9], v[112:113]
	s_nop 0
	v_addc_co_u32_e32 v31, vcc, 0, v27, vcc
	v_add_f32_e32 v88, v97, v88
	global_load_dwordx4 v[58:61], v[28:29], off nt
	global_load_dwordx4 v[46:49], v[30:31], off nt
	v_add_co_u32_e32 v28, vcc, s71, v26
	v_add_f32_e32 v88, v88, v89
	s_nop 0
	v_addc_co_u32_e32 v29, vcc, 0, v27, vcc
	v_mul_f32_e32 v89, 0xbfb8aa3b, v88
	v_add_co_u32_e32 v30, vcc, s72, v26
	v_exp_f32_e32 v89, v89
	s_nop 0
	v_addc_co_u32_e32 v31, vcc, 0, v27, vcc
	global_load_dwordx4 v[50:53], v[28:29], off nt
	global_load_dwordx4 v[38:41], v[30:31], off nt
	v_add_co_u32_e32 v28, vcc, s73, v26
	v_add_f32_e32 v89, 1.0, v89
	s_nop 0
	v_addc_co_u32_e32 v29, vcc, 0, v27, vcc
	v_add_co_u32_e32 v30, vcc, s75, v26
	v_add_f32_e32 v97, 1.0, v240
	s_nop 0
	v_addc_co_u32_e32 v31, vcc, 0, v27, vcc
	v_rcp_f32_e32 v89, v89
	global_load_dwordx4 v[42:45], v[28:29], off nt
	s_nop 0
	global_load_dwordx4 v[30:33], v[30:31], off nt
	v_add_co_u32_e32 v28, vcc, s80, v26
	v_rcp_f32_e32 v93, v239
	v_rcp_f32_e32 v97, v97
	v_addc_co_u32_e32 v29, vcc, 0, v27, vcc
	v_add_co_u32_e32 v26, vcc, s81, v26
	v_mul_f32_e32 v105, v108, v116
	s_nop 0
	v_addc_co_u32_e32 v27, vcc, 0, v27, vcc
	v_mul_f32_e32 v88, v88, v89
	v_lshlrev_b32_e32 v116, 4, v235
	global_load_dwordx4 v[34:37], v[28:29], off nt
	s_nop 0
	global_load_dwordx4 v[26:29], v[26:27], off nt
	v_mul_f32_e32 v93, v96, v93
	v_mul_f32_e32 v92, v92, v97
	v_cvt_pk_bf16_f32 v236, v236, v237
	v_cvt_pk_bf16_f32 v237, v238, v104
	v_cvt_pk_bf16_f32 v238, v105, v93
	v_cvt_pk_bf16_f32 v239, v92, v88
	v_add3_u32 v88, v234, v116, v173
	ds_write_b128 v88, v[236:239]
	v_pk_mov_b32 v[88:89], v[240:241], v[162:163] op_sel:[1,0]
	v_xor_b32_e32 v93, 64, v116
	v_pk_mul_f32 v[88:89], v[150:151], v[88:89]
	s_nop 0
	v_add_f32_e32 v88, v22, v88
	v_add_f32_e32 v92, v88, v89
	v_pk_mov_b32 v[88:89], v[242:243], v[160:161] op_sel:[1,0]
	s_nop 0
	v_pk_mul_f32 v[88:89], v[14:15], v[88:89]
	s_nop 0
	v_add_f32_e32 v88, v23, v88
	v_add_f32_e32 v96, v88, v89
	v_pk_mov_b32 v[88:89], v[244:245], v[156:157] op_sel:[1,0]
	s_nop 0
	v_pk_mul_f32 v[88:89], v[106:107], v[88:89]
	s_nop 0
	v_add_f32_e32 v88, v24, v88
	v_add_f32_e32 v104, v88, v89
	v_pk_mov_b32 v[88:89], v[246:247], v[154:155] op_sel:[1,0]
	v_add3_u32 v246, v234, v93, v173
	v_pk_mul_f32 v[88:89], v[16:17], v[88:89]
	s_nop 0
	v_add_f32_e32 v88, v25, v88
	v_add_f32_e32 v105, v88, v89
	v_pk_mov_b32 v[88:89], v[108:109], v[158:159] op_sel:[1,0]
	s_waitcnt vmcnt(13)
; __device__ __forceinline__ unsigned cvt_pk_bf16(float lo, float hi) { unsigned r; asm volatile("v_cvt_pk_bf16_f32 %0, %1, %2" : "=v"(r) : "v"(lo), "v"(hi)); return r; }
; #define LAS __attribute__((address_space(3)))
; __device__ __forceinline__ float silu_f(float x) { return x * __builtin_amdgcn_rcpf(1.f + __expf(-x)); }
; template <bool NEED_C>
; __device__ __forceinline__ void ssd_stage(LAS unsigned char* lds, const bf16_t* XBC, const float* cw, const float* cb, const float* DT, const float* a_log, int c, int g, int tid, int lane, int wave) {
;     ...
;             for (int i = 0; i < 16; ++i) { float xv[8]; unpack8(raw[3 + i], xv);
;                 float o[8];
; #pragma unroll
;                 for (int e = 0; e < 8; ++e) { o[e] = silu_f(b[e] + w[0][e] * xw[0][e] + w[1][e] * xw[1][e] + w[2][e] * xw[2][e] + w[3][e] * xv[e]); xw[0][e] = xw[1][e]; xw[1][e] = xw[2][e]; xw[2][e] = xv[e]; }
;                 u32x4 pk; pk.x = cvt_pk_bf16(o[0], o[1]); pk.y = cvt_pk_bf16(o[2], o[3]); pk.z = cvt_pk_bf16(o[4], o[5]); pk.w = cvt_pk_bf16(o[6], o[7]);
;                 *(LAS u32x4*)(tile + off_b(seg * 16 + i, tch)) = pk; }
	v_lshlrev_b32_e32 v109, 16, v82
	v_pk_mul_f32 v[88:89], v[94:95], v[88:89]
	v_lshlrev_b32_e32 v108, 16, v78
	v_add_f32_e32 v88, v10, v88
	v_add_f32_e32 v117, v88, v89
	v_pk_mov_b32 v[88:89], v[248:249], v[114:115] op_sel:[1,0]
	s_nop 0
	v_pk_mul_f32 v[88:89], v[2:3], v[88:89]
	s_nop 0
	v_add_f32_e32 v88, v11, v88
	v_add_f32_e32 v235, v88, v89
	v_pk_mov_b32 v[88:89], v[250:251], v[102:103] op_sel:[1,0]
	s_nop 0
	v_pk_mul_f32 v[88:89], v[86:87], v[88:89]
	s_nop 0
	v_add_f32_e32 v88, v12, v88
	v_add_f32_e32 v244, v88, v89
	v_pk_mov_b32 v[88:89], v[100:101], v[112:113] op_sel:[1,0]
	s_nop 0
	v_pk_mul_f32 v[88:89], v[4:5], v[88:89]
	s_nop 0
	v_add_f32_e32 v88, v13, v88
	v_add_f32_e32 v245, v88, v89
	v_pk_mul_f32 v[88:89], v[150:151], v[162:163]
	v_pk_mov_b32 v[162:163], v[162:163], v[108:109] op_sel:[1,0]
	v_add_f32_e32 v88, v22, v88
	v_add_f32_e32 v97, v88, v89
	v_pk_mul_f32 v[88:89], v[152:153], v[162:163]
	s_nop 0
	v_add_f32_e32 v88, v92, v88
	v_add_f32_e32 v100, v88, v89
	v_mul_f32_e32 v88, 0xbfb8aa3b, v100
	v_exp_f32_e32 v92, v88
	v_pk_mul_f32 v[88:89], v[152:153], v[108:109]
	s_nop 0
	v_add_f32_e32 v88, v97, v88
	v_add_f32_e32 v97, v88, v89
	v_mul_f32_e32 v88, 0xbfb8aa3b, v97
	v_exp_f32_e32 v88, v88
	v_add_f32_e32 v89, 1.0, v92
	v_rcp_f32_e32 v101, v89
	v_and_b32_e32 v89, 0xffff0000, v82
	v_add_f32_e32 v88, 1.0, v88
	v_rcp_f32_e32 v238, v88
	v_and_b32_e32 v88, 0xffff0000, v78
	v_pk_mov_b32 v[236:237], v[160:161], v[88:89] op_sel:[1,0]
	v_mul_f32_e32 v100, v100, v101
	v_pk_mul_f32 v[92:93], v[18:19], v[236:237]
	v_mul_f32_e32 v247, v97, v238
	v_add_f32_e32 v78, v96, v92
	v_add_f32_e32 v78, v78, v93
	v_mul_f32_e32 v82, 0xbfb8aa3b, v78
	v_pk_mul_f32 v[92:93], v[14:15], v[160:161]
	v_exp_f32_e32 v82, v82
	v_add_f32_e32 v92, v23, v92
	v_add_f32_e32 v96, v92, v93
	v_pk_mul_f32 v[92:93], v[18:19], v[88:89]
	v_add_f32_e32 v82, 1.0, v82
	v_add_f32_e32 v92, v96, v92
	v_add_f32_e32 v239, v92, v93
	v_mul_f32_e32 v92, 0xbfb8aa3b, v239
	v_rcp_f32_e32 v82, v82
	v_exp_f32_e32 v92, v92
	v_lshlrev_b32_e32 v97, 16, v83
	v_lshlrev_b32_e32 v96, 16, v79
	v_pk_mov_b32 v[160:161], v[156:157], v[96:97] op_sel:[1,0]
	v_mul_f32_e32 v78, v78, v82
	v_add_f32_e32 v82, 1.0, v92
	v_pk_mul_f32 v[92:93], v[110:111], v[160:161]
	v_rcp_f32_e32 v82, v82
	v_add_f32_e32 v92, v104, v92
	v_add_f32_e32 v101, v92, v93
	v_mul_f32_e32 v92, 0xbfb8aa3b, v101
	v_exp_f32_e32 v104, v92
	v_pk_mul_f32 v[92:93], v[106:107], v[156:157]
	v_mul_f32_e32 v248, v239, v82
	v_add_f32_e32 v92, v24, v92
	v_add_f32_e32 v156, v92, v93
	v_add_f32_e32 v92, 1.0, v104
	v_rcp_f32_e32 v104, v92
	v_pk_mul_f32 v[92:93], v[110:111], v[96:97]
	v_and_b32_e32 v83, 0xffff0000, v83
	v_add_f32_e32 v92, v156, v92
	v_add_f32_e32 v92, v92, v93
	v_mul_f32_e32 v93, 0xbfb8aa3b, v92
	v_exp_f32_e32 v93, v93
	v_and_b32_e32 v82, 0xffff0000, v79
	v_cvt_pk_bf16_f32 v156, v100, v78
	v_pk_mov_b32 v[238:239], v[154:155], v[82:83] op_sel:[1,0]
	v_add_f32_e32 v78, 1.0, v93
	v_rcp_f32_e32 v93, v78
	v_pk_mul_f32 v[78:79], v[20:21], v[238:239]
	v_mul_f32_e32 v100, v101, v104
	v_add_f32_e32 v78, v105, v78
	v_add_f32_e32 v101, v78, v79
	v_mul_f32_e32 v78, 0xbfb8aa3b, v101
	v_exp_f32_e32 v104, v78
	v_pk_mul_f32 v[78:79], v[16:17], v[154:155]
	v_mul_f32_e32 v249, v92, v93
	v_add_f32_e32 v78, v25, v78
	v_add_f32_e32 v105, v78, v79
	v_add_f32_e32 v78, 1.0, v104
	v_rcp_f32_e32 v104, v78
	v_pk_mul_f32 v[78:79], v[20:21], v[82:83]
	s_nop 0
	v_add_f32_e32 v78, v105, v78
	v_add_f32_e32 v240, v78, v79
	v_mul_f32_e32 v78, 0xbfb8aa3b, v240
	v_exp_f32_e32 v78, v78
	v_mul_f32_e32 v79, v101, v104
	v_cvt_pk_bf16_f32 v157, v100, v79
	v_lshlrev_b32_e32 v105, 16, v84
	v_add_f32_e32 v78, 1.0, v78
	v_rcp_f32_e32 v92, v78
	v_pk_mul_f32 v[78:79], v[94:95], v[158:159]
	v_lshlrev_b32_e32 v104, 16, v80
	v_add_f32_e32 v78, v10, v78
	v_pk_mov_b32 v[154:155], v[158:159], v[104:105] op_sel:[1,0]
	v_add_f32_e32 v93, v78, v79
	v_pk_mul_f32 v[78:79], v[98:99], v[154:155]
	v_mul_f32_e32 v250, v240, v92
	v_add_f32_e32 v78, v117, v78
	v_add_f32_e32 v100, v78, v79
	v_mul_f32_e32 v78, 0xbfb8aa3b, v100
	v_exp_f32_e32 v101, v78
	v_pk_mul_f32 v[78:79], v[98:99], v[104:105]
	s_nop 0
	v_add_f32_e32 v78, v93, v78
	v_add_f32_e32 v117, v78, v79
	v_mul_f32_e32 v78, 0xbfb8aa3b, v117
	v_exp_f32_e32 v78, v78
	v_add_f32_e32 v79, 1.0, v101
	v_rcp_f32_e32 v101, v79
	v_and_b32_e32 v79, 0xffff0000, v84
	v_add_f32_e32 v78, 1.0, v78
	v_rcp_f32_e32 v158, v78
	v_and_b32_e32 v78, 0xffff0000, v80
	v_pk_mov_b32 v[240:241], v[114:115], v[78:79] op_sel:[1,0]
	v_mul_f32_e32 v117, v117, v158
	v_pk_mul_f32 v[92:93], v[6:7], v[240:241]
	s_nop 0
	v_add_f32_e32 v80, v235, v92
	v_add_f32_e32 v80, v80, v93
	v_mul_f32_e32 v84, 0xbfb8aa3b, v80
	v_pk_mul_f32 v[92:93], v[2:3], v[114:115]
	v_exp_f32_e32 v84, v84
	v_add_f32_e32 v92, v11, v92
	v_add_f32_e32 v114, v92, v93
	v_pk_mul_f32 v[92:93], v[6:7], v[78:79]
	v_add_f32_e32 v84, 1.0, v84
	v_add_f32_e32 v92, v114, v92
	v_add_f32_e32 v114, v92, v93
	v_mul_f32_e32 v92, 0xbfb8aa3b, v114
	v_rcp_f32_e32 v84, v84
	v_exp_f32_e32 v92, v92
	v_lshlrev_b32_e32 v93, 16, v85
	v_mul_f32_e32 v115, v100, v101
	v_mul_f32_e32 v80, v80, v84
	v_add_f32_e32 v84, 1.0, v92
	v_lshlrev_b32_e32 v92, 16, v81
	v_pk_mov_b32 v[242:243], v[102:103], v[92:93] op_sel:[1,0]
	v_rcp_f32_e32 v84, v84
	v_pk_mul_f32 v[100:101], v[90:91], v[242:243]
	v_mul_f32_e32 v114, v114, v84
	v_add_f32_e32 v100, v244, v100
	v_add_f32_e32 v159, v100, v101
	v_mul_f32_e32 v100, 0xbfb8aa3b, v159
	v_exp_f32_e32 v158, v100
	v_pk_mul_f32 v[100:101], v[86:87], v[102:103]
	s_nop 0
	v_add_f32_e32 v100, v12, v100
	v_add_f32_e32 v102, v100, v101
	v_add_f32_e32 v100, 1.0, v158
	v_rcp_f32_e32 v103, v100
; __device__ __forceinline__ unsigned cvt_pk_bf16(float lo, float hi) { unsigned r; asm volatile("v_cvt_pk_bf16_f32 %0, %1, %2" : "=v"(r) : "v"(lo), "v"(hi)); return r; }
; #define LAS __attribute__((address_space(3)))
; __device__ __forceinline__ float silu_f(float x) { return x * __builtin_amdgcn_rcpf(1.f + __expf(-x)); }
; template <bool NEED_C>
; __device__ __forceinline__ void ssd_stage(LAS unsigned char* lds, const bf16_t* XBC, const float* cw, const float* cb, const float* DT, const float* a_log, int c, int g, int tid, int lane, int wave) {
;     ...
;             for (int i = 0; i < 16; ++i) { float xv[8]; unpack8(raw[3 + i], xv);
;                 float o[8];
; #pragma unroll
;                 for (int e = 0; e < 8; ++e) { o[e] = silu_f(b[e] + w[0][e] * xw[0][e] + w[1][e] * xw[1][e] + w[2][e] * xw[2][e] + w[3][e] * xv[e]); xw[0][e] = xw[1][e]; xw[1][e] = xw[2][e]; xw[2][e] = xv[e]; }
;                 u32x4 pk; pk.x = cvt_pk_bf16(o[0], o[1]); pk.y = cvt_pk_bf16(o[2], o[3]); pk.z = cvt_pk_bf16(o[4], o[5]); pk.w = cvt_pk_bf16(o[6], o[7]);
;                 *(LAS u32x4*)(tile + off_b(seg * 16 + i, tch)) = pk; }
	v_pk_mul_f32 v[100:101], v[90:91], v[92:93]
	v_cvt_pk_bf16_f32 v158, v115, v80
	v_mul_f32_e32 v103, v159, v103
	v_add_f32_e32 v100, v102, v100
	v_add_f32_e32 v102, v100, v101
	v_mul_f32_e32 v100, 0xbfb8aa3b, v102
	v_exp_f32_e32 v100, v100
	s_nop 0
	v_add_f32_e32 v80, 1.0, v100
	v_pk_mul_f32 v[100:101], v[4:5], v[112:113]
	v_rcp_f32_e32 v115, v80
	v_add_f32_e32 v80, v13, v100
	v_add_f32_e32 v159, v80, v101
	v_and_b32_e32 v101, 0xffff0000, v85
	v_and_b32_e32 v100, 0xffff0000, v81
	v_pk_mov_b32 v[80:81], v[112:113], v[100:101] op_sel:[1,0]
	v_mul_f32_e32 v102, v102, v115
	v_pk_mul_f32 v[84:85], v[8:9], v[80:81]
	v_pk_mul_f32 v[80:81], v[4:5], v[80:81]
	v_add_f32_e32 v84, v245, v84
	v_add_f32_e32 v112, v84, v85
	v_mul_f32_e32 v84, 0xbfb8aa3b, v112
	v_exp_f32_e32 v113, v84
	v_pk_mul_f32 v[84:85], v[8:9], v[100:101]
	v_add_f32_e32 v80, v13, v80
	v_add_f32_e32 v84, v159, v84
	v_add_f32_e32 v84, v84, v85
	v_mul_f32_e32 v85, 0xbfb8aa3b, v84
	v_exp_f32_e32 v85, v85
	v_add_f32_e32 v113, 1.0, v113
	v_rcp_f32_e32 v113, v113
	v_add_f32_e32 v85, 1.0, v85
	v_rcp_f32_e32 v85, v85
	v_mul_f32_e32 v112, v112, v113
	v_cvt_pk_bf16_f32 v159, v103, v112
	ds_write_b128 v246, v[156:159] offset:256
	v_mul_f32_e32 v84, v84, v85
	v_cvt_pk_bf16_f32 v112, v247, v248
	v_cvt_pk_bf16_f32 v113, v249, v250
	v_cvt_pk_bf16_f32 v114, v117, v114
	v_cvt_pk_bf16_f32 v115, v102, v84
	v_xor_b32_e32 v84, 0x80, v116
	v_add3_u32 v84, v234, v84, v173
	ds_write_b128 v84, v[112:115] offset:512
	v_pk_mul_f32 v[84:85], v[150:151], v[162:163]
	v_add_f32_e32 v163, v80, v81
	v_add_f32_e32 v84, v22, v84
	v_add_f32_e32 v112, v84, v85
	v_pk_mul_f32 v[84:85], v[14:15], v[236:237]
	v_pk_mul_f32 v[80:81], v[150:151], v[108:109]
	v_add_f32_e32 v84, v23, v84
	v_add_f32_e32 v113, v84, v85
	v_pk_mul_f32 v[84:85], v[106:107], v[160:161]
	s_waitcnt vmcnt(11)
	v_lshlrev_b32_e32 v103, 16, v74
	v_add_f32_e32 v84, v24, v84
	v_add_f32_e32 v114, v84, v85
	v_pk_mul_f32 v[84:85], v[16:17], v[238:239]
	v_lshlrev_b32_e32 v102, 16, v70
	v_add_f32_e32 v84, v25, v84
	v_add_f32_e32 v115, v84, v85
	v_pk_mul_f32 v[84:85], v[94:95], v[154:155]
	v_add_f32_e32 v80, v22, v80
	v_add_f32_e32 v84, v10, v84
	v_add_f32_e32 v117, v84, v85
	v_pk_mul_f32 v[84:85], v[2:3], v[240:241]
	v_pk_mov_b32 v[108:109], v[108:109], v[102:103] op_sel:[1,0]
	v_add_f32_e32 v84, v11, v84
	v_add_f32_e32 v160, v84, v85
	v_pk_mul_f32 v[84:85], v[86:87], v[242:243]
	s_nop 0
	v_add_f32_e32 v84, v12, v84
	v_add_f32_e32 v162, v84, v85
	v_add_f32_e32 v85, v80, v81
	v_pk_mul_f32 v[80:81], v[152:153], v[108:109]
	v_xor_b32_e32 v84, 0xc0, v116
	v_add_f32_e32 v80, v112, v80
	v_add_f32_e32 v112, v80, v81
	v_mul_f32_e32 v80, 0xbfb8aa3b, v112
	v_exp_f32_e32 v154, v80
	v_pk_mul_f32 v[80:81], v[152:153], v[102:103]
	v_add3_u32 v235, v234, v84, v173
	v_add_f32_e32 v80, v85, v80
	v_add_f32_e32 v156, v80, v81
	v_mul_f32_e32 v80, 0xbfb8aa3b, v156
	v_exp_f32_e32 v80, v80
	v_add_f32_e32 v81, 1.0, v154
	v_rcp_f32_e32 v157, v81
	v_and_b32_e32 v81, 0xffff0000, v74
	v_add_f32_e32 v80, 1.0, v80
	v_rcp_f32_e32 v158, v80
	v_and_b32_e32 v80, 0xffff0000, v70
	v_pk_mov_b32 v[154:155], v[88:89], v[80:81] op_sel:[1,0]
	v_mul_f32_e32 v157, v112, v157
	v_pk_mul_f32 v[84:85], v[18:19], v[154:155]
	v_mul_f32_e32 v236, v156, v158
	v_add_f32_e32 v70, v113, v84
	v_add_f32_e32 v70, v70, v85
	v_mul_f32_e32 v74, 0xbfb8aa3b, v70
	v_pk_mul_f32 v[84:85], v[14:15], v[88:89]
	v_exp_f32_e32 v74, v74
	v_add_f32_e32 v84, v23, v84
	v_add_f32_e32 v88, v84, v85
	v_pk_mul_f32 v[84:85], v[18:19], v[80:81]
	v_add_f32_e32 v74, 1.0, v74
	v_add_f32_e32 v84, v88, v84
	v_add_f32_e32 v159, v84, v85
	v_mul_f32_e32 v84, 0xbfb8aa3b, v159
	v_rcp_f32_e32 v74, v74
	v_exp_f32_e32 v84, v84
	v_lshlrev_b32_e32 v85, 16, v75
	v_and_b32_e32 v75, 0xffff0000, v75
	v_mul_f32_e32 v70, v70, v74
	v_add_f32_e32 v74, 1.0, v84
	v_lshlrev_b32_e32 v84, 16, v71
	v_pk_mov_b32 v[88:89], v[96:97], v[84:85] op_sel:[1,0]
	v_pk_mul_f32 v[96:97], v[106:107], v[96:97]
	v_pk_mul_f32 v[112:113], v[110:111], v[88:89]
	v_add_f32_e32 v96, v24, v96
	v_add_f32_e32 v112, v114, v112
	v_add_f32_e32 v113, v112, v113
	v_mul_f32_e32 v112, 0xbfb8aa3b, v113
	v_exp_f32_e32 v112, v112
	v_add_f32_e32 v114, v96, v97
	v_rcp_f32_e32 v74, v74
	v_add_f32_e32 v96, 1.0, v112
	v_rcp_f32_e32 v156, v96
	v_pk_mul_f32 v[96:97], v[110:111], v[84:85]
	v_mul_f32_e32 v237, v159, v74
	v_add_f32_e32 v96, v114, v96
	v_add_f32_e32 v96, v96, v97
	v_mul_f32_e32 v97, 0xbfb8aa3b, v96
	v_exp_f32_e32 v97, v97
	v_and_b32_e32 v74, 0xffff0000, v71
	v_cvt_pk_bf16_f32 v112, v157, v70
	v_mul_f32_e32 v113, v113, v156
	v_add_f32_e32 v70, 1.0, v97
	v_pk_mov_b32 v[156:157], v[82:83], v[74:75] op_sel:[1,0]
	v_rcp_f32_e32 v97, v70
	v_pk_mul_f32 v[70:71], v[20:21], v[156:157]
	v_mul_f32_e32 v238, v96, v97
	v_add_f32_e32 v70, v115, v70
	v_add_f32_e32 v114, v70, v71
	v_mul_f32_e32 v70, 0xbfb8aa3b, v114
	v_exp_f32_e32 v115, v70
	v_pk_mul_f32 v[70:71], v[16:17], v[82:83]
	v_lshlrev_b32_e32 v97, 16, v76
	v_add_f32_e32 v70, v25, v70
	v_add_f32_e32 v82, v70, v71
	v_add_f32_e32 v70, 1.0, v115
	v_rcp_f32_e32 v83, v70
	v_pk_mul_f32 v[70:71], v[20:21], v[74:75]
	v_lshlrev_b32_e32 v96, 16, v72
	v_add_f32_e32 v70, v82, v70
	v_add_f32_e32 v82, v70, v71
	v_mul_f32_e32 v70, 0xbfb8aa3b, v82
	v_exp_f32_e32 v70, v70
	v_mul_f32_e32 v71, v114, v83
	v_cvt_pk_bf16_f32 v113, v113, v71
	v_add_f32_e32 v70, 1.0, v70
	v_rcp_f32_e32 v83, v70
	v_pk_mul_f32 v[70:71], v[94:95], v[104:105]
	v_pk_mov_b32 v[104:105], v[104:105], v[96:97] op_sel:[1,0]
	v_add_f32_e32 v70, v10, v70
	v_add_f32_e32 v114, v70, v71
	v_pk_mul_f32 v[70:71], v[98:99], v[104:105]
	v_mul_f32_e32 v239, v82, v83
	v_add_f32_e32 v70, v117, v70
	v_add_f32_e32 v115, v70, v71
; __device__ __forceinline__ unsigned cvt_pk_bf16(float lo, float hi) { unsigned r; asm volatile("v_cvt_pk_bf16_f32 %0, %1, %2" : "=v"(r) : "v"(lo), "v"(hi)); return r; }
; #define LAS __attribute__((address_space(3)))
; __device__ __forceinline__ float silu_f(float x) { return x * __builtin_amdgcn_rcpf(1.f + __expf(-x)); }
; template <bool NEED_C>
; __device__ __forceinline__ void ssd_stage(LAS unsigned char* lds, const bf16_t* XBC, const float* cw, const float* cb, const float* DT, const float* a_log, int c, int g, int tid, int lane, int wave) {
;     ...
;             for (int i = 0; i < 16; ++i) { float xv[8]; unpack8(raw[3 + i], xv);
;                 float o[8];
; #pragma unroll
;                 for (int e = 0; e < 8; ++e) { o[e] = silu_f(b[e] + w[0][e] * xw[0][e] + w[1][e] * xw[1][e] + w[2][e] * xw[2][e] + w[3][e] * xv[e]); xw[0][e] = xw[1][e]; xw[1][e] = xw[2][e]; xw[2][e] = xv[e]; }
;                 u32x4 pk; pk.x = cvt_pk_bf16(o[0], o[1]); pk.y = cvt_pk_bf16(o[2], o[3]); pk.z = cvt_pk_bf16(o[4], o[5]); pk.w = cvt_pk_bf16(o[6], o[7]);
;                 *(LAS u32x4*)(tile + off_b(seg * 16 + i, tch)) = pk; }
	v_mul_f32_e32 v70, 0xbfb8aa3b, v115
	v_exp_f32_e32 v117, v70
	v_pk_mul_f32 v[70:71], v[98:99], v[96:97]
	s_nop 0
	v_add_f32_e32 v70, v114, v70
	v_add_f32_e32 v114, v70, v71
	v_mul_f32_e32 v70, 0xbfb8aa3b, v114
	v_exp_f32_e32 v70, v70
	v_add_f32_e32 v71, 1.0, v117
	v_rcp_f32_e32 v117, v71
	v_and_b32_e32 v71, 0xffff0000, v76
	v_add_f32_e32 v70, 1.0, v70
	v_rcp_f32_e32 v161, v70
	v_and_b32_e32 v70, 0xffff0000, v72
	v_pk_mov_b32 v[158:159], v[78:79], v[70:71] op_sel:[1,0]
	v_pk_mul_f32 v[78:79], v[2:3], v[78:79]
	v_pk_mul_f32 v[82:83], v[6:7], v[158:159]
	v_add_f32_e32 v78, v11, v78
	v_add_f32_e32 v72, v160, v82
	v_add_f32_e32 v72, v72, v83
	v_mul_f32_e32 v76, 0xbfb8aa3b, v72
	v_exp_f32_e32 v76, v76
	v_add_f32_e32 v82, v78, v79
	v_pk_mul_f32 v[78:79], v[6:7], v[70:71]
	v_mul_f32_e32 v115, v115, v117
	v_add_f32_e32 v78, v82, v78
	v_add_f32_e32 v240, v78, v79
	v_add_f32_e32 v76, 1.0, v76
	v_mul_f32_e32 v78, 0xbfb8aa3b, v240
	v_rcp_f32_e32 v76, v76
	v_exp_f32_e32 v78, v78
	v_lshlrev_b32_e32 v79, 16, v77
	v_mul_f32_e32 v117, v114, v161
	v_mul_f32_e32 v72, v72, v76
	v_add_f32_e32 v76, 1.0, v78
	v_lshlrev_b32_e32 v78, 16, v73
	v_pk_mov_b32 v[160:161], v[92:93], v[78:79] op_sel:[1,0]
	v_rcp_f32_e32 v76, v76
	v_pk_mul_f32 v[82:83], v[90:91], v[160:161]
	v_mul_f32_e32 v240, v240, v76
	v_add_f32_e32 v82, v162, v82
	v_add_f32_e32 v162, v82, v83
	v_mul_f32_e32 v82, 0xbfb8aa3b, v162
	v_exp_f32_e32 v114, v82
	v_pk_mul_f32 v[82:83], v[86:87], v[92:93]
	s_nop 0
	v_add_f32_e32 v82, v12, v82
	v_add_f32_e32 v92, v82, v83
	v_add_f32_e32 v82, 1.0, v114
	v_rcp_f32_e32 v93, v82
	v_pk_mul_f32 v[82:83], v[90:91], v[78:79]
	v_cvt_pk_bf16_f32 v114, v115, v72
	v_mul_f32_e32 v93, v162, v93
	v_add_f32_e32 v82, v92, v82
	v_add_f32_e32 v92, v82, v83
	v_mul_f32_e32 v82, 0xbfb8aa3b, v92
	v_exp_f32_e32 v82, v82
	s_nop 0
	v_add_f32_e32 v72, 1.0, v82
	v_pk_mul_f32 v[82:83], v[4:5], v[100:101]
	v_rcp_f32_e32 v115, v72
	v_add_f32_e32 v72, v13, v82
	v_add_f32_e32 v162, v72, v83
	v_and_b32_e32 v83, 0xffff0000, v77
	v_and_b32_e32 v82, 0xffff0000, v73
	v_pk_mov_b32 v[72:73], v[100:101], v[82:83] op_sel:[1,0]
	v_mul_f32_e32 v92, v92, v115
	v_pk_mul_f32 v[76:77], v[8:9], v[72:73]
	v_pk_mul_f32 v[72:73], v[4:5], v[72:73]
	v_add_f32_e32 v76, v163, v76
	v_add_f32_e32 v100, v76, v77
	v_mul_f32_e32 v76, 0xbfb8aa3b, v100
	v_exp_f32_e32 v101, v76
	v_pk_mul_f32 v[76:77], v[8:9], v[82:83]
	v_add_f32_e32 v72, v13, v72
	v_add_f32_e32 v76, v162, v76
	v_add_f32_e32 v76, v76, v77
	v_mul_f32_e32 v77, 0xbfb8aa3b, v76
	v_exp_f32_e32 v77, v77
	v_add_f32_e32 v101, 1.0, v101
	v_rcp_f32_e32 v101, v101
	v_add_f32_e32 v77, 1.0, v77
	v_rcp_f32_e32 v77, v77
	v_mul_f32_e32 v100, v100, v101
	v_cvt_pk_bf16_f32 v115, v93, v100
	ds_write_b128 v235, v[112:115] offset:768
	v_mul_f32_e32 v76, v76, v77
	v_cvt_pk_bf16_f32 v112, v236, v237
	v_cvt_pk_bf16_f32 v113, v238, v239
	v_cvt_pk_bf16_f32 v114, v117, v240
	v_cvt_pk_bf16_f32 v115, v92, v76
	v_xor_b32_e32 v76, 16, v116
	v_add3_u32 v76, v234, v76, v173
	ds_write_b128 v76, v[112:115] offset:1024
	v_pk_mul_f32 v[76:77], v[150:151], v[108:109]
	s_nop 0
	v_add_f32_e32 v76, v22, v76
	v_add_f32_e32 v100, v76, v77
	v_pk_mul_f32 v[76:77], v[14:15], v[154:155]
	s_nop 0
	v_add_f32_e32 v76, v23, v76
	v_add_f32_e32 v101, v76, v77
	v_pk_mul_f32 v[76:77], v[106:107], v[88:89]
	s_waitcnt vmcnt(9)
	v_lshlrev_b32_e32 v89, 16, v66
	v_add_f32_e32 v76, v24, v76
	v_add_f32_e32 v112, v76, v77
	v_pk_mul_f32 v[76:77], v[16:17], v[156:157]
	v_add_f32_e32 v157, v72, v73
	v_add_f32_e32 v76, v25, v76
	v_add_f32_e32 v114, v76, v77
	v_pk_mul_f32 v[76:77], v[94:95], v[104:105]
	v_pk_mul_f32 v[72:73], v[150:151], v[102:103]
	v_add_f32_e32 v76, v10, v76
	v_add_f32_e32 v115, v76, v77
	v_pk_mul_f32 v[76:77], v[2:3], v[158:159]
	v_lshlrev_b32_e32 v88, 16, v62
	v_add_f32_e32 v76, v11, v76
	v_add_f32_e32 v117, v76, v77
	v_pk_mul_f32 v[76:77], v[86:87], v[160:161]
	v_add_f32_e32 v72, v22, v72
	v_add_f32_e32 v76, v12, v76
	v_pk_mov_b32 v[92:93], v[102:103], v[88:89] op_sel:[1,0]
	v_add_f32_e32 v156, v76, v77
	v_add_f32_e32 v77, v72, v73
	v_pk_mul_f32 v[72:73], v[152:153], v[92:93]
	v_xor_b32_e32 v76, 0x50, v116
	v_add_f32_e32 v72, v100, v72
	v_add_f32_e32 v100, v72, v73
	v_mul_f32_e32 v72, 0xbfb8aa3b, v100
	v_exp_f32_e32 v102, v72
	v_pk_mul_f32 v[72:73], v[152:153], v[88:89]
	v_add3_u32 v158, v234, v76, v173
	v_add_f32_e32 v72, v77, v72
	v_add_f32_e32 v103, v72, v73
	v_mul_f32_e32 v72, 0xbfb8aa3b, v103
	v_exp_f32_e32 v72, v72
	v_add_f32_e32 v73, 1.0, v102
	v_rcp_f32_e32 v102, v73
	v_and_b32_e32 v73, 0xffff0000, v66
	v_add_f32_e32 v72, 1.0, v72
	v_rcp_f32_e32 v108, v72
	v_and_b32_e32 v72, 0xffff0000, v62
	v_pk_mov_b32 v[104:105], v[80:81], v[72:73] op_sel:[1,0]
	v_mul_f32_e32 v100, v100, v102
	v_pk_mul_f32 v[76:77], v[18:19], v[104:105]
	v_mul_f32_e32 v159, v103, v108
	v_add_f32_e32 v62, v101, v76
	v_add_f32_e32 v62, v62, v77
	v_mul_f32_e32 v66, 0xbfb8aa3b, v62
	v_pk_mul_f32 v[76:77], v[14:15], v[80:81]
	v_exp_f32_e32 v66, v66
	v_add_f32_e32 v76, v23, v76
	v_add_f32_e32 v80, v76, v77
	v_pk_mul_f32 v[76:77], v[18:19], v[72:73]
	v_add_f32_e32 v66, 1.0, v66
	v_add_f32_e32 v76, v80, v76
	v_add_f32_e32 v101, v76, v77
	v_mul_f32_e32 v76, 0xbfb8aa3b, v101
	v_rcp_f32_e32 v66, v66
	v_exp_f32_e32 v76, v76
	v_lshlrev_b32_e32 v77, 16, v67
	v_and_b32_e32 v67, 0xffff0000, v67
	v_mul_f32_e32 v62, v62, v66
	v_add_f32_e32 v66, 1.0, v76
	v_lshlrev_b32_e32 v76, 16, v63
	v_pk_mov_b32 v[108:109], v[84:85], v[76:77] op_sel:[1,0]
	v_rcp_f32_e32 v66, v66
	v_pk_mul_f32 v[80:81], v[110:111], v[108:109]
	v_cvt_pk_bf16_f32 v100, v100, v62
	s_nop 0
	v_add_f32_e32 v80, v112, v80
	v_add_f32_e32 v102, v80, v81
	v_mul_f32_e32 v80, 0xbfb8aa3b, v102
; __device__ __forceinline__ unsigned cvt_pk_bf16(float lo, float hi) { unsigned r; asm volatile("v_cvt_pk_bf16_f32 %0, %1, %2" : "=v"(r) : "v"(lo), "v"(hi)); return r; }
; #define LAS __attribute__((address_space(3)))
; __device__ __forceinline__ float silu_f(float x) { return x * __builtin_amdgcn_rcpf(1.f + __expf(-x)); }
; template <bool NEED_C>
; __device__ __forceinline__ void ssd_stage(LAS unsigned char* lds, const bf16_t* XBC, const float* cw, const float* cb, const float* DT, const float* a_log, int c, int g, int tid, int lane, int wave) {
;     ...
;             for (int i = 0; i < 16; ++i) { float xv[8]; unpack8(raw[3 + i], xv);
;                 float o[8];
; #pragma unroll
;                 for (int e = 0; e < 8; ++e) { o[e] = silu_f(b[e] + w[0][e] * xw[0][e] + w[1][e] * xw[1][e] + w[2][e] * xw[2][e] + w[3][e] * xv[e]); xw[0][e] = xw[1][e]; xw[1][e] = xw[2][e]; xw[2][e] = xv[e]; }
;                 u32x4 pk; pk.x = cvt_pk_bf16(o[0], o[1]); pk.y = cvt_pk_bf16(o[2], o[3]); pk.z = cvt_pk_bf16(o[4], o[5]); pk.w = cvt_pk_bf16(o[6], o[7]);
;                 *(LAS u32x4*)(tile + off_b(seg * 16 + i, tch)) = pk; }
	v_exp_f32_e32 v103, v80
	v_pk_mul_f32 v[80:81], v[106:107], v[84:85]
	s_nop 0
	v_add_f32_e32 v80, v24, v80
	v_add_f32_e32 v84, v80, v81
	v_add_f32_e32 v80, 1.0, v103
	v_rcp_f32_e32 v85, v80
	v_pk_mul_f32 v[80:81], v[110:111], v[76:77]
	v_mul_f32_e32 v85, v102, v85
	v_add_f32_e32 v80, v84, v80
	v_add_f32_e32 v80, v80, v81
	v_mul_f32_e32 v81, 0xbfb8aa3b, v80
	v_exp_f32_e32 v81, v81
	v_mul_f32_e32 v84, v101, v66
	v_and_b32_e32 v66, 0xffff0000, v63
	v_pk_mov_b32 v[112:113], v[74:75], v[66:67] op_sel:[1,0]
	v_add_f32_e32 v62, 1.0, v81
	v_rcp_f32_e32 v81, v62
	v_pk_mul_f32 v[62:63], v[20:21], v[112:113]
	v_mul_f32_e32 v160, v80, v81
	v_add_f32_e32 v62, v114, v62
	v_add_f32_e32 v101, v62, v63
	v_mul_f32_e32 v62, 0xbfb8aa3b, v101
	v_exp_f32_e32 v102, v62
	v_pk_mul_f32 v[62:63], v[16:17], v[74:75]
	v_lshlrev_b32_e32 v81, 16, v68
	v_add_f32_e32 v62, v25, v62
	v_add_f32_e32 v74, v62, v63
	v_add_f32_e32 v62, 1.0, v102
	v_rcp_f32_e32 v75, v62
	v_pk_mul_f32 v[62:63], v[20:21], v[66:67]
	v_lshlrev_b32_e32 v80, 16, v64
	v_add_f32_e32 v62, v74, v62
	v_add_f32_e32 v74, v62, v63
	v_mul_f32_e32 v62, 0xbfb8aa3b, v74
	v_exp_f32_e32 v62, v62
	v_mul_f32_e32 v63, v101, v75
	v_cvt_pk_bf16_f32 v101, v85, v63
	v_add_f32_e32 v62, 1.0, v62
	v_rcp_f32_e32 v75, v62
	v_pk_mul_f32 v[62:63], v[94:95], v[96:97]
	v_pk_mov_b32 v[96:97], v[96:97], v[80:81] op_sel:[1,0]
	v_add_f32_e32 v62, v10, v62
	v_add_f32_e32 v85, v62, v63
	v_pk_mul_f32 v[62:63], v[98:99], v[96:97]
	v_mul_f32_e32 v161, v74, v75
	v_add_f32_e32 v62, v115, v62
	v_add_f32_e32 v102, v62, v63
	v_mul_f32_e32 v62, 0xbfb8aa3b, v102
	v_exp_f32_e32 v103, v62
	v_pk_mul_f32 v[62:63], v[98:99], v[80:81]
	s_nop 0
	v_add_f32_e32 v62, v85, v62
	v_add_f32_e32 v85, v62, v63
	v_mul_f32_e32 v62, 0xbfb8aa3b, v85
	v_exp_f32_e32 v62, v62
	v_add_f32_e32 v63, 1.0, v103
	v_rcp_f32_e32 v103, v63
	v_and_b32_e32 v63, 0xffff0000, v68
	v_add_f32_e32 v62, 1.0, v62
	v_rcp_f32_e32 v154, v62
	v_and_b32_e32 v62, 0xffff0000, v64
	v_pk_mov_b32 v[114:115], v[70:71], v[62:63] op_sel:[1,0]
	v_pk_mul_f32 v[70:71], v[2:3], v[70:71]
	v_pk_mul_f32 v[74:75], v[6:7], v[114:115]
	v_add_f32_e32 v70, v11, v70
	v_add_f32_e32 v64, v117, v74
	v_add_f32_e32 v64, v64, v75
	v_mul_f32_e32 v68, 0xbfb8aa3b, v64
	v_exp_f32_e32 v68, v68
	v_add_f32_e32 v74, v70, v71
	v_pk_mul_f32 v[70:71], v[6:7], v[62:63]
	v_mul_f32_e32 v85, v85, v154
	v_add_f32_e32 v70, v74, v70
	v_add_f32_e32 v117, v70, v71
	v_add_f32_e32 v68, 1.0, v68
	v_mul_f32_e32 v70, 0xbfb8aa3b, v117
	v_rcp_f32_e32 v68, v68
	v_exp_f32_e32 v70, v70
	v_lshlrev_b32_e32 v71, 16, v69
	v_mul_f32_e32 v102, v102, v103
	v_mul_f32_e32 v64, v64, v68
	v_add_f32_e32 v68, 1.0, v70
	v_lshlrev_b32_e32 v70, 16, v65
	v_pk_mov_b32 v[154:155], v[78:79], v[70:71] op_sel:[1,0]
	v_rcp_f32_e32 v68, v68
	v_pk_mul_f32 v[74:75], v[90:91], v[154:155]
	v_cvt_pk_bf16_f32 v102, v102, v64
	v_mul_f32_e32 v117, v117, v68
	v_add_f32_e32 v74, v156, v74
	v_add_f32_e32 v103, v74, v75
	v_mul_f32_e32 v74, 0xbfb8aa3b, v103
	v_exp_f32_e32 v156, v74
	v_pk_mul_f32 v[74:75], v[86:87], v[78:79]
	s_nop 0
	v_add_f32_e32 v74, v12, v74
	v_add_f32_e32 v78, v74, v75
	v_add_f32_e32 v74, 1.0, v156
	v_rcp_f32_e32 v79, v74
	v_pk_mul_f32 v[74:75], v[90:91], v[70:71]
	v_mul_f32_e32 v79, v103, v79
	v_add_f32_e32 v74, v78, v74
	v_add_f32_e32 v78, v74, v75
	v_mul_f32_e32 v74, 0xbfb8aa3b, v78
	v_exp_f32_e32 v74, v74
	s_nop 0
	v_add_f32_e32 v64, 1.0, v74
	v_pk_mul_f32 v[74:75], v[4:5], v[82:83]
	v_rcp_f32_e32 v103, v64
	v_add_f32_e32 v64, v13, v74
	v_add_f32_e32 v156, v64, v75
	v_and_b32_e32 v75, 0xffff0000, v69
	v_and_b32_e32 v74, 0xffff0000, v65
	v_pk_mov_b32 v[64:65], v[82:83], v[74:75] op_sel:[1,0]
	v_mul_f32_e32 v78, v78, v103
	v_pk_mul_f32 v[68:69], v[8:9], v[64:65]
	v_pk_mul_f32 v[64:65], v[4:5], v[64:65]
	v_add_f32_e32 v68, v157, v68
	v_add_f32_e32 v82, v68, v69
	v_mul_f32_e32 v68, 0xbfb8aa3b, v82
	v_exp_f32_e32 v83, v68
	v_pk_mul_f32 v[68:69], v[8:9], v[74:75]
	v_add_f32_e32 v64, v13, v64
	v_add_f32_e32 v68, v156, v68
	v_add_f32_e32 v68, v68, v69
	v_mul_f32_e32 v69, 0xbfb8aa3b, v68
	v_exp_f32_e32 v69, v69
	v_add_f32_e32 v83, 1.0, v83
	v_rcp_f32_e32 v83, v83
	v_add_f32_e32 v69, 1.0, v69
	v_rcp_f32_e32 v69, v69
	v_mul_f32_e32 v82, v82, v83
	v_cvt_pk_bf16_f32 v103, v79, v82
	ds_write_b128 v158, v[100:103] offset:1280
	v_mul_f32_e32 v68, v68, v69
	v_cvt_pk_bf16_f32 v82, v159, v84
	v_cvt_pk_bf16_f32 v83, v160, v161
	v_cvt_pk_bf16_f32 v84, v85, v117
	v_cvt_pk_bf16_f32 v85, v78, v68
	v_xor_b32_e32 v68, 0x90, v116
	v_add3_u32 v68, v234, v68, v173
	ds_write_b128 v68, v[82:85] offset:1536
	v_pk_mul_f32 v[68:69], v[150:151], v[92:93]
	s_waitcnt vmcnt(7)
; __device__ __forceinline__ unsigned cvt_pk_bf16(float lo, float hi) { unsigned r; asm volatile("v_cvt_pk_bf16_f32 %0, %1, %2" : "=v"(r) : "v"(lo), "v"(hi)); return r; }
; #define LAS __attribute__((address_space(3)))
; __device__ __forceinline__ float silu_f(float x) { return x * __builtin_amdgcn_rcpf(1.f + __expf(-x)); }
; template <bool NEED_C>
; __device__ __forceinline__ void ssd_stage(LAS unsigned char* lds, const bf16_t* XBC, const float* cw, const float* cb, const float* DT, const float* a_log, int c, int g, int tid, int lane, int wave) {
;     ...
;             for (int i = 0; i < 16; ++i) { float xv[8]; unpack8(raw[3 + i], xv);
;                 float o[8];
; #pragma unroll
;                 for (int e = 0; e < 8; ++e) { o[e] = silu_f(b[e] + w[0][e] * xw[0][e] + w[1][e] * xw[1][e] + w[2][e] * xw[2][e] + w[3][e] * xv[e]); xw[0][e] = xw[1][e]; xw[1][e] = xw[2][e]; xw[2][e] = xv[e]; }
;                 u32x4 pk; pk.x = cvt_pk_bf16(o[0], o[1]); pk.y = cvt_pk_bf16(o[2], o[3]); pk.z = cvt_pk_bf16(o[4], o[5]); pk.w = cvt_pk_bf16(o[6], o[7]);
;                 *(LAS u32x4*)(tile + off_b(seg * 16 + i, tch)) = pk; }
	v_lshlrev_b32_e32 v79, 16, v58
	v_add_f32_e32 v68, v22, v68
	v_add_f32_e32 v82, v68, v69
	v_pk_mul_f32 v[68:69], v[14:15], v[104:105]
	v_add_f32_e32 v105, v64, v65
	v_add_f32_e32 v68, v23, v68
	v_add_f32_e32 v83, v68, v69
	v_pk_mul_f32 v[68:69], v[106:107], v[108:109]
	v_pk_mul_f32 v[64:65], v[150:151], v[88:89]
	v_add_f32_e32 v68, v24, v68
	v_add_f32_e32 v84, v68, v69
	v_pk_mul_f32 v[68:69], v[16:17], v[112:113]
	v_lshlrev_b32_e32 v78, 16, v54
	v_add_f32_e32 v68, v25, v68
	v_add_f32_e32 v85, v68, v69
	v_pk_mul_f32 v[68:69], v[94:95], v[96:97]
	v_add_f32_e32 v64, v22, v64
	v_add_f32_e32 v68, v10, v68
	v_add_f32_e32 v100, v68, v69
	v_pk_mul_f32 v[68:69], v[2:3], v[114:115]
	v_pk_mov_b32 v[88:89], v[88:89], v[78:79] op_sel:[1,0]
	v_add_f32_e32 v68, v11, v68
	v_add_f32_e32 v102, v68, v69
	v_pk_mul_f32 v[68:69], v[86:87], v[154:155]
	s_nop 0
	v_add_f32_e32 v68, v12, v68
	v_add_f32_e32 v104, v68, v69
	v_add_f32_e32 v69, v64, v65
	v_pk_mul_f32 v[64:65], v[152:153], v[88:89]
	v_xor_b32_e32 v68, 0xd0, v116
	v_add_f32_e32 v64, v82, v64
	v_add_f32_e32 v82, v64, v65
	v_mul_f32_e32 v64, 0xbfb8aa3b, v82
	v_exp_f32_e32 v92, v64
	v_pk_mul_f32 v[64:65], v[152:153], v[78:79]
	v_add3_u32 v108, v234, v68, v173
	v_add_f32_e32 v64, v69, v64
	v_add_f32_e32 v96, v64, v65
	v_mul_f32_e32 v64, 0xbfb8aa3b, v96
	v_exp_f32_e32 v64, v64
	v_add_f32_e32 v65, 1.0, v92
	v_rcp_f32_e32 v97, v65
	v_and_b32_e32 v65, 0xffff0000, v58
	v_add_f32_e32 v64, 1.0, v64
	v_rcp_f32_e32 v101, v64
	v_and_b32_e32 v64, 0xffff0000, v54
	v_pk_mov_b32 v[92:93], v[72:73], v[64:65] op_sel:[1,0]
	v_mul_f32_e32 v97, v82, v97
	v_pk_mul_f32 v[68:69], v[18:19], v[92:93]
	v_mul_f32_e32 v109, v96, v101
	v_add_f32_e32 v54, v83, v68
	v_add_f32_e32 v54, v54, v69
	v_mul_f32_e32 v58, 0xbfb8aa3b, v54
	v_pk_mul_f32 v[68:69], v[14:15], v[72:73]
	v_exp_f32_e32 v58, v58
	v_add_f32_e32 v68, v23, v68
	v_add_f32_e32 v72, v68, v69
	v_pk_mul_f32 v[68:69], v[18:19], v[64:65]
	v_add_f32_e32 v58, 1.0, v58
	v_add_f32_e32 v68, v72, v68
	v_add_f32_e32 v103, v68, v69
	v_mul_f32_e32 v68, 0xbfb8aa3b, v103
	v_rcp_f32_e32 v58, v58
	v_exp_f32_e32 v68, v68
	v_lshlrev_b32_e32 v69, 16, v59
	v_and_b32_e32 v59, 0xffff0000, v59
	v_mul_f32_e32 v54, v54, v58
	v_add_f32_e32 v58, 1.0, v68
	v_lshlrev_b32_e32 v68, 16, v55
	v_pk_mov_b32 v[72:73], v[76:77], v[68:69] op_sel:[1,0]
	v_pk_mul_f32 v[76:77], v[106:107], v[76:77]
	v_pk_mul_f32 v[82:83], v[110:111], v[72:73]
	v_add_f32_e32 v76, v24, v76
	v_add_f32_e32 v82, v84, v82
	v_add_f32_e32 v83, v82, v83
	v_mul_f32_e32 v82, 0xbfb8aa3b, v83
	v_exp_f32_e32 v82, v82
	v_add_f32_e32 v84, v76, v77
	v_rcp_f32_e32 v58, v58
	v_add_f32_e32 v76, 1.0, v82
	v_rcp_f32_e32 v96, v76
	v_pk_mul_f32 v[76:77], v[110:111], v[68:69]
	v_mul_f32_e32 v112, v103, v58
	v_add_f32_e32 v76, v84, v76
	v_add_f32_e32 v76, v76, v77
	v_mul_f32_e32 v77, 0xbfb8aa3b, v76
	v_exp_f32_e32 v77, v77
	v_and_b32_e32 v58, 0xffff0000, v55
	v_cvt_pk_bf16_f32 v82, v97, v54
	v_mul_f32_e32 v83, v83, v96
	v_add_f32_e32 v54, 1.0, v77
	v_pk_mov_b32 v[96:97], v[66:67], v[58:59] op_sel:[1,0]
	v_rcp_f32_e32 v77, v54
	v_pk_mul_f32 v[54:55], v[20:21], v[96:97]
	v_mul_f32_e32 v113, v76, v77
	v_add_f32_e32 v54, v85, v54
	v_add_f32_e32 v84, v54, v55
	v_mul_f32_e32 v54, 0xbfb8aa3b, v84
	v_exp_f32_e32 v85, v54
	v_pk_mul_f32 v[54:55], v[16:17], v[66:67]
	v_lshlrev_b32_e32 v77, 16, v60
	v_add_f32_e32 v54, v25, v54
	v_add_f32_e32 v66, v54, v55
	v_add_f32_e32 v54, 1.0, v85
	v_rcp_f32_e32 v67, v54
	v_pk_mul_f32 v[54:55], v[20:21], v[58:59]
	v_lshlrev_b32_e32 v76, 16, v56
	v_add_f32_e32 v54, v66, v54
	v_add_f32_e32 v66, v54, v55
	v_mul_f32_e32 v54, 0xbfb8aa3b, v66
	v_exp_f32_e32 v54, v54
	v_mul_f32_e32 v55, v84, v67
	v_cvt_pk_bf16_f32 v83, v83, v55
	v_add_f32_e32 v54, 1.0, v54
	v_rcp_f32_e32 v67, v54
	v_pk_mul_f32 v[54:55], v[94:95], v[80:81]
	v_pk_mov_b32 v[80:81], v[80:81], v[76:77] op_sel:[1,0]
	v_add_f32_e32 v54, v10, v54
	v_add_f32_e32 v84, v54, v55
	v_pk_mul_f32 v[54:55], v[98:99], v[80:81]
	v_mul_f32_e32 v114, v66, v67
	v_add_f32_e32 v54, v100, v54
	v_add_f32_e32 v85, v54, v55
	v_mul_f32_e32 v54, 0xbfb8aa3b, v85
	v_exp_f32_e32 v100, v54
	v_pk_mul_f32 v[54:55], v[98:99], v[76:77]
	s_nop 0
	v_add_f32_e32 v54, v84, v54
	v_add_f32_e32 v84, v54, v55
	v_mul_f32_e32 v54, 0xbfb8aa3b, v84
	v_exp_f32_e32 v54, v54
	v_add_f32_e32 v55, 1.0, v100
	v_rcp_f32_e32 v103, v55
	v_and_b32_e32 v55, 0xffff0000, v60
	v_add_f32_e32 v54, 1.0, v54
	v_rcp_f32_e32 v115, v54
	v_and_b32_e32 v54, 0xffff0000, v56
	v_pk_mov_b32 v[100:101], v[62:63], v[54:55] op_sel:[1,0]
	v_pk_mul_f32 v[62:63], v[2:3], v[62:63]
	v_pk_mul_f32 v[66:67], v[6:7], v[100:101]
	v_add_f32_e32 v62, v11, v62
	v_add_f32_e32 v56, v102, v66
	v_add_f32_e32 v56, v56, v67
	v_mul_f32_e32 v60, 0xbfb8aa3b, v56
	v_exp_f32_e32 v60, v60
	v_add_f32_e32 v66, v62, v63
	v_pk_mul_f32 v[62:63], v[6:7], v[54:55]
	v_lshlrev_b32_e32 v67, 16, v61
	v_add_f32_e32 v62, v66, v62
	v_add_f32_e32 v117, v62, v63
	v_add_f32_e32 v60, 1.0, v60
	v_mul_f32_e32 v62, 0xbfb8aa3b, v117
	v_rcp_f32_e32 v60, v60
	v_exp_f32_e32 v62, v62
	v_lshlrev_b32_e32 v66, 16, v57
	v_mul_f32_e32 v85, v85, v103
	v_pk_mov_b32 v[102:103], v[70:71], v[66:67] op_sel:[1,0]
	v_mul_f32_e32 v56, v56, v60
	v_add_f32_e32 v60, 1.0, v62
	v_pk_mul_f32 v[62:63], v[90:91], v[102:103]
	v_mul_f32_e32 v115, v84, v115
	v_add_f32_e32 v62, v104, v62
	v_add_f32_e32 v104, v62, v63
	v_mul_f32_e32 v62, 0xbfb8aa3b, v104
	v_exp_f32_e32 v84, v62
	v_pk_mul_f32 v[62:63], v[86:87], v[70:71]
	v_rcp_f32_e32 v60, v60
	v_add_f32_e32 v62, v12, v62
	v_add_f32_e32 v70, v62, v63
	v_add_f32_e32 v62, 1.0, v84
	v_rcp_f32_e32 v71, v62
	v_pk_mul_f32 v[62:63], v[90:91], v[66:67]
	v_cvt_pk_bf16_f32 v84, v85, v56
; __device__ __forceinline__ unsigned cvt_pk_bf16(float lo, float hi) { unsigned r; asm volatile("v_cvt_pk_bf16_f32 %0, %1, %2" : "=v"(r) : "v"(lo), "v"(hi)); return r; }
; #define LAS __attribute__((address_space(3)))
; __device__ __forceinline__ float silu_f(float x) { return x * __builtin_amdgcn_rcpf(1.f + __expf(-x)); }
; template <bool NEED_C>
; __device__ __forceinline__ void ssd_stage(LAS unsigned char* lds, const bf16_t* XBC, const float* cw, const float* cb, const float* DT, const float* a_log, int c, int g, int tid, int lane, int wave) {
;     ...
;             for (int i = 0; i < 16; ++i) { float xv[8]; unpack8(raw[3 + i], xv);
;                 float o[8];
; #pragma unroll
;                 for (int e = 0; e < 8; ++e) { o[e] = silu_f(b[e] + w[0][e] * xw[0][e] + w[1][e] * xw[1][e] + w[2][e] * xw[2][e] + w[3][e] * xv[e]); xw[0][e] = xw[1][e]; xw[1][e] = xw[2][e]; xw[2][e] = xv[e]; }
;                 u32x4 pk; pk.x = cvt_pk_bf16(o[0], o[1]); pk.y = cvt_pk_bf16(o[2], o[3]); pk.z = cvt_pk_bf16(o[4], o[5]); pk.w = cvt_pk_bf16(o[6], o[7]);
;                 *(LAS u32x4*)(tile + off_b(seg * 16 + i, tch)) = pk; }
	v_mul_f32_e32 v117, v117, v60
	v_add_f32_e32 v62, v70, v62
	v_add_f32_e32 v154, v62, v63
	v_mul_f32_e32 v62, 0xbfb8aa3b, v154
	v_exp_f32_e32 v62, v62
	v_mul_f32_e32 v85, v104, v71
	v_and_b32_e32 v71, 0xffff0000, v61
	v_and_b32_e32 v70, 0xffff0000, v57
	v_add_f32_e32 v56, 1.0, v62
	v_pk_mul_f32 v[62:63], v[4:5], v[74:75]
	v_rcp_f32_e32 v104, v56
	v_add_f32_e32 v56, v13, v62
	v_add_f32_e32 v62, v56, v63
	v_pk_mov_b32 v[56:57], v[74:75], v[70:71] op_sel:[1,0]
	s_nop 0
	v_pk_mul_f32 v[60:61], v[8:9], v[56:57]
	v_pk_mul_f32 v[56:57], v[4:5], v[56:57]
	v_add_f32_e32 v60, v105, v60
	v_add_f32_e32 v63, v60, v61
	v_mul_f32_e32 v60, 0xbfb8aa3b, v63
	v_exp_f32_e32 v74, v60
	v_pk_mul_f32 v[60:61], v[8:9], v[70:71]
	v_add_f32_e32 v56, v13, v56
	v_add_f32_e32 v60, v62, v60
	v_add_f32_e32 v60, v60, v61
	v_mul_f32_e32 v61, 0xbfb8aa3b, v60
	v_exp_f32_e32 v61, v61
	v_add_f32_e32 v62, 1.0, v74
	v_rcp_f32_e32 v62, v62
	v_mul_f32_e32 v74, v154, v104
	v_add_f32_e32 v61, 1.0, v61
	v_rcp_f32_e32 v61, v61
	v_mul_f32_e32 v62, v63, v62
	v_cvt_pk_bf16_f32 v85, v85, v62
	ds_write_b128 v108, v[82:85] offset:1792
	v_mul_f32_e32 v63, v60, v61
	v_cvt_pk_bf16_f32 v60, v109, v112
	v_cvt_pk_bf16_f32 v61, v113, v114
	v_cvt_pk_bf16_f32 v62, v115, v117
	v_cvt_pk_bf16_f32 v63, v74, v63
	v_xor_b32_e32 v74, 32, v116
	v_add3_u32 v74, v234, v74, v173
	ds_write_b128 v74, v[60:63] offset:2048
	v_pk_mul_f32 v[60:61], v[150:151], v[88:89]
	v_add_f32_e32 v89, v56, v57
	v_add_f32_e32 v60, v22, v60
	v_add_f32_e32 v62, v60, v61
	v_pk_mul_f32 v[60:61], v[14:15], v[92:93]
	v_pk_mul_f32 v[56:57], v[150:151], v[78:79]
	v_add_f32_e32 v60, v23, v60
	v_add_f32_e32 v63, v60, v61
	v_pk_mul_f32 v[60:61], v[106:107], v[72:73]
	s_waitcnt vmcnt(5)
	v_lshlrev_b32_e32 v73, 16, v50
	v_add_f32_e32 v60, v24, v60
	v_add_f32_e32 v82, v60, v61
	v_pk_mul_f32 v[60:61], v[16:17], v[96:97]
	v_lshlrev_b32_e32 v72, 16, v46
	v_add_f32_e32 v60, v25, v60
	v_add_f32_e32 v83, v60, v61
	v_pk_mul_f32 v[60:61], v[94:95], v[80:81]
	v_add_f32_e32 v56, v22, v56
	v_add_f32_e32 v60, v10, v60
	v_add_f32_e32 v80, v60, v61
	v_pk_mul_f32 v[60:61], v[2:3], v[100:101]
	v_pk_mov_b32 v[74:75], v[78:79], v[72:73] op_sel:[1,0]
	v_add_f32_e32 v60, v11, v60
	v_add_f32_e32 v84, v60, v61
	v_pk_mul_f32 v[60:61], v[86:87], v[102:103]
	s_nop 0
	v_add_f32_e32 v60, v12, v60
	v_add_f32_e32 v88, v60, v61
	v_add_f32_e32 v61, v56, v57
	v_pk_mul_f32 v[56:57], v[152:153], v[74:75]
	v_xor_b32_e32 v60, 0x60, v116
	v_add_f32_e32 v56, v62, v56
	v_add_f32_e32 v62, v56, v57
	v_mul_f32_e32 v56, 0xbfb8aa3b, v62
	v_exp_f32_e32 v78, v56
	v_pk_mul_f32 v[56:57], v[152:153], v[72:73]
	v_add3_u32 v92, v234, v60, v173
	v_add_f32_e32 v56, v61, v56
	v_add_f32_e32 v81, v56, v57
	v_mul_f32_e32 v56, 0xbfb8aa3b, v81
	v_exp_f32_e32 v56, v56
	v_add_f32_e32 v57, 1.0, v78
	v_rcp_f32_e32 v85, v57
	v_and_b32_e32 v57, 0xffff0000, v50
	v_add_f32_e32 v56, 1.0, v56
	v_rcp_f32_e32 v93, v56
	v_and_b32_e32 v56, 0xffff0000, v46
	v_pk_mov_b32 v[78:79], v[64:65], v[56:57] op_sel:[1,0]
	v_mul_f32_e32 v85, v62, v85
	v_pk_mul_f32 v[60:61], v[18:19], v[78:79]
	v_lshlrev_b32_e32 v62, 16, v47
	v_add_f32_e32 v46, v63, v60
	v_add_f32_e32 v46, v46, v61
	v_mul_f32_e32 v50, 0xbfb8aa3b, v46
	v_pk_mul_f32 v[60:61], v[14:15], v[64:65]
	v_exp_f32_e32 v50, v50
	v_add_f32_e32 v60, v23, v60
	v_add_f32_e32 v63, v60, v61
	v_pk_mul_f32 v[60:61], v[18:19], v[56:57]
	v_add_f32_e32 v50, 1.0, v50
	v_add_f32_e32 v60, v63, v60
	v_add_f32_e32 v96, v60, v61
	v_mul_f32_e32 v60, 0xbfb8aa3b, v96
	v_rcp_f32_e32 v50, v50
	v_exp_f32_e32 v60, v60
	v_lshlrev_b32_e32 v63, 16, v51
	v_pk_mov_b32 v[64:65], v[68:69], v[62:63] op_sel:[1,0]
	v_mul_f32_e32 v46, v46, v50
	v_add_f32_e32 v50, 1.0, v60
	v_pk_mul_f32 v[60:61], v[110:111], v[64:65]
	v_mul_f32_e32 v93, v81, v93
	v_add_f32_e32 v60, v82, v60
	v_add_f32_e32 v81, v60, v61
	v_mul_f32_e32 v60, 0xbfb8aa3b, v81
	v_exp_f32_e32 v82, v60
	v_pk_mul_f32 v[60:61], v[106:107], v[68:69]
	v_rcp_f32_e32 v50, v50
	v_add_f32_e32 v60, v24, v60
	v_add_f32_e32 v68, v60, v61
	v_add_f32_e32 v60, 1.0, v82
	v_rcp_f32_e32 v69, v60
	v_pk_mul_f32 v[60:61], v[110:111], v[62:63]
	v_mul_f32_e32 v96, v96, v50
	v_add_f32_e32 v60, v68, v60
	v_add_f32_e32 v82, v60, v61
	v_mul_f32_e32 v60, 0xbfb8aa3b, v82
	v_exp_f32_e32 v60, v60
	v_and_b32_e32 v61, 0xffff0000, v51
	v_cvt_pk_bf16_f32 v46, v85, v46
	v_mul_f32_e32 v81, v81, v69
	v_add_f32_e32 v50, 1.0, v60
	v_and_b32_e32 v60, 0xffff0000, v47
	v_rcp_f32_e32 v85, v50
	v_pk_mov_b32 v[50:51], v[58:59], v[60:61] op_sel:[1,0]
	v_pk_mul_f32 v[58:59], v[16:17], v[58:59]
	v_pk_mul_f32 v[68:69], v[20:21], v[50:51]
	v_add_f32_e32 v58, v25, v58
	v_add_f32_e32 v47, v83, v68
	v_add_f32_e32 v47, v47, v69
	v_mul_f32_e32 v68, 0xbfb8aa3b, v47
	v_exp_f32_e32 v68, v68
	v_add_f32_e32 v69, v58, v59
	v_mul_f32_e32 v97, v82, v85
	v_add_f32_e32 v58, 1.0, v68
	v_rcp_f32_e32 v68, v58
	v_pk_mul_f32 v[58:59], v[20:21], v[60:61]
	v_mul_f32_e32 v47, v47, v68
	v_add_f32_e32 v58, v69, v58
	v_add_f32_e32 v83, v58, v59
	v_mul_f32_e32 v58, 0xbfb8aa3b, v83
	v_exp_f32_e32 v58, v58
	v_cvt_pk_bf16_f32 v47, v81, v47
	v_lshlrev_b32_e32 v69, 16, v52
	v_lshlrev_b32_e32 v68, 16, v48
	v_add_f32_e32 v58, 1.0, v58
	v_rcp_f32_e32 v81, v58
	v_pk_mul_f32 v[58:59], v[94:95], v[76:77]
	v_pk_mov_b32 v[76:77], v[76:77], v[68:69] op_sel:[1,0]
	v_add_f32_e32 v58, v10, v58
	v_add_f32_e32 v82, v58, v59
	v_pk_mul_f32 v[58:59], v[98:99], v[76:77]
	v_mul_f32_e32 v101, v83, v81
	v_add_f32_e32 v58, v80, v58
	v_add_f32_e32 v85, v58, v59
	v_mul_f32_e32 v58, 0xbfb8aa3b, v85
	v_exp_f32_e32 v80, v58
	v_pk_mul_f32 v[58:59], v[98:99], v[68:69]
	s_nop 0
	v_add_f32_e32 v58, v82, v58
	v_add_f32_e32 v100, v58, v59
; __device__ __forceinline__ unsigned cvt_pk_bf16(float lo, float hi) { unsigned r; asm volatile("v_cvt_pk_bf16_f32 %0, %1, %2" : "=v"(r) : "v"(lo), "v"(hi)); return r; }
; #define LAS __attribute__((address_space(3)))
; __device__ __forceinline__ float silu_f(float x) { return x * __builtin_amdgcn_rcpf(1.f + __expf(-x)); }
; template <bool NEED_C>
; __device__ __forceinline__ void ssd_stage(LAS unsigned char* lds, const bf16_t* XBC, const float* cw, const float* cb, const float* DT, const float* a_log, int c, int g, int tid, int lane, int wave) {
;     ...
;             for (int i = 0; i < 16; ++i) { float xv[8]; unpack8(raw[3 + i], xv);
;                 float o[8];
; #pragma unroll
;                 for (int e = 0; e < 8; ++e) { o[e] = silu_f(b[e] + w[0][e] * xw[0][e] + w[1][e] * xw[1][e] + w[2][e] * xw[2][e] + w[3][e] * xv[e]); xw[0][e] = xw[1][e]; xw[1][e] = xw[2][e]; xw[2][e] = xv[e]; }
;                 u32x4 pk; pk.x = cvt_pk_bf16(o[0], o[1]); pk.y = cvt_pk_bf16(o[2], o[3]); pk.z = cvt_pk_bf16(o[4], o[5]); pk.w = cvt_pk_bf16(o[6], o[7]);
;                 *(LAS u32x4*)(tile + off_b(seg * 16 + i, tch)) = pk; }
	v_mul_f32_e32 v58, 0xbfb8aa3b, v100
	v_exp_f32_e32 v58, v58
	v_add_f32_e32 v59, 1.0, v80
	v_rcp_f32_e32 v102, v59
	v_and_b32_e32 v59, 0xffff0000, v52
	v_add_f32_e32 v58, 1.0, v58
	v_rcp_f32_e32 v103, v58
	v_and_b32_e32 v58, 0xffff0000, v48
	v_pk_mov_b32 v[80:81], v[54:55], v[58:59] op_sel:[1,0]
	v_pk_mul_f32 v[54:55], v[2:3], v[54:55]
	v_pk_mul_f32 v[82:83], v[6:7], v[80:81]
	v_add_f32_e32 v54, v11, v54
	v_add_f32_e32 v48, v84, v82
	v_add_f32_e32 v48, v48, v83
	v_mul_f32_e32 v52, 0xbfb8aa3b, v48
	v_exp_f32_e32 v52, v52
	v_add_f32_e32 v82, v54, v55
	v_pk_mul_f32 v[54:55], v[6:7], v[58:59]
	v_mul_f32_e32 v102, v85, v102
	v_add_f32_e32 v54, v82, v54
	v_add_f32_e32 v104, v54, v55
	v_add_f32_e32 v52, 1.0, v52
	v_mul_f32_e32 v54, 0xbfb8aa3b, v104
	v_rcp_f32_e32 v52, v52
	v_exp_f32_e32 v54, v54
	v_lshlrev_b32_e32 v55, 16, v53
	v_mul_f32_e32 v100, v100, v103
	v_mul_f32_e32 v48, v48, v52
	v_add_f32_e32 v52, 1.0, v54
	v_lshlrev_b32_e32 v54, 16, v49
	v_pk_mov_b32 v[82:83], v[66:67], v[54:55] op_sel:[1,0]
	v_pk_mul_f32 v[66:67], v[86:87], v[66:67]
	v_pk_mul_f32 v[84:85], v[90:91], v[82:83]
	v_add_f32_e32 v66, v12, v66
	v_add_f32_e32 v84, v88, v84
	v_add_f32_e32 v84, v84, v85
	v_mul_f32_e32 v85, 0xbfb8aa3b, v84
	v_exp_f32_e32 v85, v85
	v_add_f32_e32 v88, v66, v67
	v_rcp_f32_e32 v52, v52
	v_cvt_pk_bf16_f32 v48, v102, v48
	v_add_f32_e32 v66, 1.0, v85
	v_rcp_f32_e32 v85, v66
	v_pk_mul_f32 v[66:67], v[90:91], v[54:55]
	v_mul_f32_e32 v102, v104, v52
	v_add_f32_e32 v66, v88, v66
	v_add_f32_e32 v88, v66, v67
	v_mul_f32_e32 v66, 0xbfb8aa3b, v88
	v_exp_f32_e32 v66, v66
	v_mul_f32_e32 v84, v84, v85
	v_add_f32_e32 v52, 1.0, v66
	v_pk_mul_f32 v[66:67], v[4:5], v[70:71]
	v_rcp_f32_e32 v85, v52
	v_add_f32_e32 v52, v13, v66
	v_add_f32_e32 v103, v52, v67
	v_and_b32_e32 v67, 0xffff0000, v53
	v_and_b32_e32 v66, 0xffff0000, v49
	v_pk_mov_b32 v[52:53], v[70:71], v[66:67] op_sel:[1,0]
	v_mul_f32_e32 v85, v88, v85
	v_pk_mul_f32 v[70:71], v[8:9], v[52:53]
	s_nop 0
	v_add_f32_e32 v49, v89, v70
	v_add_f32_e32 v49, v49, v71
	v_mul_f32_e32 v70, 0xbfb8aa3b, v49
	v_exp_f32_e32 v89, v70
	v_pk_mul_f32 v[70:71], v[8:9], v[66:67]
	v_add_f32_e32 v89, 1.0, v89
	v_add_f32_e32 v70, v103, v70
	v_add_f32_e32 v70, v70, v71
	v_mul_f32_e32 v71, 0xbfb8aa3b, v70
	v_exp_f32_e32 v71, v71
	v_rcp_f32_e32 v89, v89
	v_add_f32_e32 v71, 1.0, v71
	v_rcp_f32_e32 v71, v71
	v_mul_f32_e32 v49, v49, v89
	v_cvt_pk_bf16_f32 v49, v84, v49
	ds_write_b128 v92, v[46:49] offset:2304
	v_mul_f32_e32 v49, v70, v71
	v_xor_b32_e32 v70, 0xa0, v116
	v_cvt_pk_bf16_f32 v46, v93, v96
	v_cvt_pk_bf16_f32 v47, v97, v101
	v_add3_u32 v70, v234, v70, v173
	v_cvt_pk_bf16_f32 v48, v100, v102
	v_cvt_pk_bf16_f32 v49, v85, v49
	ds_write_b128 v70, v[46:49] offset:2560
	v_pk_mul_f32 v[46:47], v[150:151], v[74:75]
	s_nop 0
	v_add_f32_e32 v46, v22, v46
	v_add_f32_e32 v48, v46, v47
	v_pk_mul_f32 v[46:47], v[14:15], v[78:79]
	s_nop 0
	v_add_f32_e32 v46, v23, v46
	v_add_f32_e32 v49, v46, v47
	v_pk_mul_f32 v[46:47], v[106:107], v[64:65]
	s_waitcnt vmcnt(3)
	v_lshlrev_b32_e32 v65, 16, v42
	v_add_f32_e32 v46, v24, v46
	v_add_f32_e32 v78, v46, v47
	v_pk_mul_f32 v[46:47], v[16:17], v[50:51]
	v_lshlrev_b32_e32 v64, 16, v38
	v_add_f32_e32 v46, v25, v46
	v_add_f32_e32 v79, v46, v47
	v_pk_mul_f32 v[46:47], v[94:95], v[76:77]
	v_pk_mov_b32 v[70:71], v[72:73], v[64:65] op_sel:[1,0]
	v_add_f32_e32 v46, v10, v46
	v_add_f32_e32 v76, v46, v47
	v_pk_mul_f32 v[46:47], v[2:3], v[80:81]
	v_xor_b32_e32 v50, 0xe0, v116
	v_add_f32_e32 v46, v11, v46
	v_add_f32_e32 v77, v46, v47
	v_pk_mul_f32 v[46:47], v[86:87], v[82:83]
	v_add3_u32 v82, v234, v50, v173
	v_add_f32_e32 v46, v12, v46
	v_add_f32_e32 v80, v46, v47
	v_pk_mul_f32 v[46:47], v[4:5], v[52:53]
	v_and_b32_e32 v50, 0xffff0000, v38
	v_add_f32_e32 v46, v13, v46
	v_add_f32_e32 v81, v46, v47
	v_pk_mul_f32 v[46:47], v[150:151], v[72:73]
	s_nop 0
	v_add_f32_e32 v46, v22, v46
	v_add_f32_e32 v51, v46, v47
	v_pk_mul_f32 v[46:47], v[152:153], v[70:71]
	s_nop 0
	v_add_f32_e32 v46, v48, v46
	v_add_f32_e32 v48, v46, v47
	v_mul_f32_e32 v46, 0xbfb8aa3b, v48
	v_exp_f32_e32 v52, v46
	v_pk_mul_f32 v[46:47], v[152:153], v[64:65]
	s_nop 0
	v_add_f32_e32 v46, v51, v46
	v_add_f32_e32 v53, v46, v47
	v_mul_f32_e32 v46, 0xbfb8aa3b, v53
	v_exp_f32_e32 v46, v46
	v_and_b32_e32 v51, 0xffff0000, v42
	v_add_f32_e32 v47, 1.0, v52
	v_pk_mov_b32 v[72:73], v[56:57], v[50:51] op_sel:[1,0]
	v_add_f32_e32 v46, 1.0, v46
	v_rcp_f32_e32 v52, v47
	v_rcp_f32_e32 v74, v46
	v_pk_mul_f32 v[46:47], v[18:19], v[72:73]
	v_mul_f32_e32 v52, v48, v52
	v_add_f32_e32 v38, v49, v46
	v_add_f32_e32 v38, v38, v47
	v_mul_f32_e32 v42, 0xbfb8aa3b, v38
	v_pk_mul_f32 v[46:47], v[14:15], v[56:57]
	v_exp_f32_e32 v42, v42
	v_add_f32_e32 v46, v23, v46
	v_add_f32_e32 v49, v46, v47
	v_pk_mul_f32 v[46:47], v[18:19], v[50:51]
	v_add_f32_e32 v42, 1.0, v42
	v_add_f32_e32 v46, v49, v46
	v_add_f32_e32 v57, v46, v47
	v_mul_f32_e32 v46, 0xbfb8aa3b, v57
	v_rcp_f32_e32 v42, v42
	v_exp_f32_e32 v46, v46
	v_lshlrev_b32_e32 v49, 16, v43
	v_lshlrev_b32_e32 v48, 16, v39
	v_mul_f32_e32 v83, v53, v74
	v_pk_mov_b32 v[74:75], v[62:63], v[48:49] op_sel:[1,0]
	v_mul_f32_e32 v38, v38, v42
	v_add_f32_e32 v42, 1.0, v46
	v_pk_mul_f32 v[46:47], v[110:111], v[74:75]
	v_rcp_f32_e32 v42, v42
	v_add_f32_e32 v46, v78, v46
	v_add_f32_e32 v53, v46, v47
	v_mul_f32_e32 v46, 0xbfb8aa3b, v53
	v_exp_f32_e32 v56, v46
	v_pk_mul_f32 v[46:47], v[106:107], v[62:63]
	v_mul_f32_e32 v84, v57, v42
	v_add_f32_e32 v46, v24, v46
	v_add_f32_e32 v62, v46, v47
	v_add_f32_e32 v46, 1.0, v56
	v_rcp_f32_e32 v63, v46
	v_pk_mul_f32 v[46:47], v[110:111], v[48:49]
	v_cvt_pk_bf16_f32 v56, v52, v38
	v_mul_f32_e32 v42, v53, v63
; __device__ __forceinline__ unsigned cvt_pk_bf16(float lo, float hi) { unsigned r; asm volatile("v_cvt_pk_bf16_f32 %0, %1, %2" : "=v"(r) : "v"(lo), "v"(hi)); return r; }
; #define LAS __attribute__((address_space(3)))
; __device__ __forceinline__ float silu_f(float x) { return x * __builtin_amdgcn_rcpf(1.f + __expf(-x)); }
; template <bool NEED_C>
; __device__ __forceinline__ void ssd_stage(LAS unsigned char* lds, const bf16_t* XBC, const float* cw, const float* cb, const float* DT, const float* a_log, int c, int g, int tid, int lane, int wave) {
;     ...
;             for (int i = 0; i < 16; ++i) { float xv[8]; unpack8(raw[3 + i], xv);
;                 float o[8];
; #pragma unroll
;                 for (int e = 0; e < 8; ++e) { o[e] = silu_f(b[e] + w[0][e] * xw[0][e] + w[1][e] * xw[1][e] + w[2][e] * xw[2][e] + w[3][e] * xv[e]); xw[0][e] = xw[1][e]; xw[1][e] = xw[2][e]; xw[2][e] = xv[e]; }
;                 u32x4 pk; pk.x = cvt_pk_bf16(o[0], o[1]); pk.y = cvt_pk_bf16(o[2], o[3]); pk.z = cvt_pk_bf16(o[4], o[5]); pk.w = cvt_pk_bf16(o[6], o[7]);
;                 *(LAS u32x4*)(tile + off_b(seg * 16 + i, tch)) = pk; }
	v_add_f32_e32 v46, v62, v46
	v_add_f32_e32 v78, v46, v47
	v_mul_f32_e32 v46, 0xbfb8aa3b, v78
	v_exp_f32_e32 v46, v46
	v_and_b32_e32 v47, 0xffff0000, v43
	v_add_f32_e32 v38, 1.0, v46
	v_and_b32_e32 v46, 0xffff0000, v39
	v_pk_mov_b32 v[62:63], v[60:61], v[46:47] op_sel:[1,0]
	v_rcp_f32_e32 v52, v38
	v_pk_mul_f32 v[38:39], v[20:21], v[62:63]
	v_mul_f32_e32 v78, v78, v52
	v_add_f32_e32 v38, v79, v38
	v_add_f32_e32 v43, v38, v39
	v_mul_f32_e32 v38, 0xbfb8aa3b, v43
	v_exp_f32_e32 v53, v38
	v_pk_mul_f32 v[38:39], v[16:17], v[60:61]
	v_lshlrev_b32_e32 v52, 16, v40
	v_add_f32_e32 v38, v25, v38
	v_add_f32_e32 v57, v38, v39
	v_add_f32_e32 v38, 1.0, v53
	v_rcp_f32_e32 v53, v38
	v_pk_mul_f32 v[38:39], v[20:21], v[46:47]
	s_nop 0
	v_add_f32_e32 v38, v57, v38
	v_add_f32_e32 v79, v38, v39
	v_mul_f32_e32 v38, 0xbfb8aa3b, v79
	v_exp_f32_e32 v38, v38
	v_mul_f32_e32 v39, v43, v53
	v_cvt_pk_bf16_f32 v57, v42, v39
	v_lshlrev_b32_e32 v53, 16, v44
	v_add_f32_e32 v38, 1.0, v38
	v_rcp_f32_e32 v42, v38
	v_pk_mul_f32 v[38:39], v[94:95], v[68:69]
	v_pk_mov_b32 v[60:61], v[68:69], v[52:53] op_sel:[1,0]
	v_add_f32_e32 v38, v10, v38
	v_add_f32_e32 v43, v38, v39
	v_pk_mul_f32 v[38:39], v[98:99], v[60:61]
	v_mul_f32_e32 v79, v79, v42
	v_add_f32_e32 v38, v76, v38
	v_add_f32_e32 v76, v38, v39
	v_mul_f32_e32 v38, 0xbfb8aa3b, v76
	v_exp_f32_e32 v68, v38
	v_pk_mul_f32 v[38:39], v[98:99], v[52:53]
	v_and_b32_e32 v42, 0xffff0000, v40
	v_add_f32_e32 v38, v43, v38
	v_add_f32_e32 v85, v38, v39
	v_mul_f32_e32 v38, 0xbfb8aa3b, v85
	v_exp_f32_e32 v38, v38
	v_and_b32_e32 v43, 0xffff0000, v44
	v_add_f32_e32 v39, 1.0, v68
	v_pk_mov_b32 v[68:69], v[58:59], v[42:43] op_sel:[1,0]
	v_add_f32_e32 v38, 1.0, v38
	v_rcp_f32_e32 v88, v39
	v_rcp_f32_e32 v89, v38
	v_pk_mul_f32 v[38:39], v[6:7], v[68:69]
	v_mul_f32_e32 v88, v76, v88
	v_add_f32_e32 v38, v77, v38
	v_add_f32_e32 v40, v38, v39
	v_mul_f32_e32 v38, 0xbfb8aa3b, v40
	v_exp_f32_e32 v44, v38
	v_pk_mul_f32 v[38:39], v[2:3], v[58:59]
	v_mul_f32_e32 v85, v85, v89
	v_add_f32_e32 v38, v11, v38
	v_add_f32_e32 v58, v38, v39
	v_add_f32_e32 v38, 1.0, v44
	v_rcp_f32_e32 v44, v38
	v_pk_mul_f32 v[38:39], v[6:7], v[42:43]
	v_mul_f32_e32 v40, v40, v44
	v_add_f32_e32 v38, v58, v38
	v_add_f32_e32 v92, v38, v39
	v_mul_f32_e32 v38, 0xbfb8aa3b, v92
	v_exp_f32_e32 v38, v38
	v_lshlrev_b32_e32 v39, 16, v45
	v_and_b32_e32 v45, 0xffff0000, v45
	v_add_f32_e32 v38, 1.0, v38
	v_rcp_f32_e32 v44, v38
	v_lshlrev_b32_e32 v38, 16, v41
	v_pk_mov_b32 v[76:77], v[54:55], v[38:39] op_sel:[1,0]
	v_pk_mul_f32 v[54:55], v[86:87], v[54:55]
	v_pk_mul_f32 v[58:59], v[90:91], v[76:77]
	v_add_f32_e32 v54, v12, v54
	v_add_f32_e32 v58, v80, v58
	v_add_f32_e32 v59, v58, v59
	v_mul_f32_e32 v58, 0xbfb8aa3b, v59
	v_exp_f32_e32 v58, v58
	v_add_f32_e32 v80, v54, v55
	v_add_f32_e32 v54, 1.0, v58
	v_rcp_f32_e32 v89, v54
	v_pk_mul_f32 v[54:55], v[90:91], v[38:39]
	v_cvt_pk_bf16_f32 v58, v88, v40
	v_mul_f32_e32 v88, v92, v44
	v_add_f32_e32 v54, v80, v54
	v_add_f32_e32 v80, v54, v55
	v_mul_f32_e32 v54, 0xbfb8aa3b, v80
	v_exp_f32_e32 v54, v54
	v_mul_f32_e32 v59, v59, v89
	v_and_b32_e32 v44, 0xffff0000, v41
	v_add_f32_e32 v40, 1.0, v54
	v_pk_mul_f32 v[54:55], v[4:5], v[66:67]
	v_rcp_f32_e32 v89, v40
	v_add_f32_e32 v40, v13, v54
	v_add_f32_e32 v92, v40, v55
	v_pk_mov_b32 v[40:41], v[66:67], v[44:45] op_sel:[1,0]
	v_mul_f32_e32 v80, v80, v89
	v_pk_mul_f32 v[54:55], v[8:9], v[40:41]
	v_pk_mul_f32 v[40:41], v[4:5], v[40:41]
	v_add_f32_e32 v54, v81, v54
	v_add_f32_e32 v66, v54, v55
	v_mul_f32_e32 v54, 0xbfb8aa3b, v66
	v_exp_f32_e32 v67, v54
	v_pk_mul_f32 v[54:55], v[8:9], v[44:45]
	v_add_f32_e32 v40, v13, v40
	v_add_f32_e32 v54, v92, v54
	v_add_f32_e32 v54, v54, v55
	v_mul_f32_e32 v55, 0xbfb8aa3b, v54
	v_exp_f32_e32 v55, v55
	v_add_f32_e32 v67, 1.0, v67
	v_rcp_f32_e32 v67, v67
	v_add_f32_e32 v55, 1.0, v55
	v_rcp_f32_e32 v55, v55
	v_mul_f32_e32 v66, v66, v67
	v_cvt_pk_bf16_f32 v59, v59, v66
	ds_write_b128 v82, v[56:59] offset:2816
	v_xor_b32_e32 v58, 48, v116
	v_mul_f32_e32 v57, v54, v55
	v_cvt_pk_bf16_f32 v54, v83, v84
	v_cvt_pk_bf16_f32 v55, v78, v79
	v_add3_u32 v58, v234, v58, v173
	v_cvt_pk_bf16_f32 v56, v85, v88
	v_cvt_pk_bf16_f32 v57, v80, v57
	ds_write_b128 v58, v[54:57] offset:3072
	v_pk_mul_f32 v[54:55], v[150:151], v[70:71]
	v_xor_b32_e32 v59, 0x70, v116
	v_add_f32_e32 v54, v22, v54
	v_add_f32_e32 v58, v54, v55
	v_pk_mul_f32 v[54:55], v[14:15], v[72:73]
	v_add_f32_e32 v73, v40, v41
	v_add_f32_e32 v54, v23, v54
	v_add_f32_e32 v66, v54, v55
	v_pk_mul_f32 v[54:55], v[106:107], v[74:75]
	v_pk_mul_f32 v[40:41], v[150:151], v[64:65]
	v_add_f32_e32 v54, v24, v54
	v_add_f32_e32 v67, v54, v55
	v_pk_mul_f32 v[54:55], v[16:17], v[62:63]
	v_add_f32_e32 v40, v22, v40
	v_add_f32_e32 v54, v25, v54
	v_add_f32_e32 v70, v54, v55
	v_pk_mul_f32 v[54:55], v[94:95], v[60:61]
	v_add_f32_e32 v60, v40, v41
	v_add_f32_e32 v54, v10, v54
	v_add_f32_e32 v71, v54, v55
	v_pk_mul_f32 v[54:55], v[2:3], v[68:69]
	s_waitcnt vmcnt(2)
	v_lshlrev_b32_e32 v40, 16, v30
	v_add_f32_e32 v54, v11, v54
	v_add_f32_e32 v68, v54, v55
	v_pk_mul_f32 v[54:55], v[86:87], v[76:77]
	s_waitcnt vmcnt(1)
; __device__ __forceinline__ unsigned cvt_pk_bf16(float lo, float hi) { unsigned r; asm volatile("v_cvt_pk_bf16_f32 %0, %1, %2" : "=v"(r) : "v"(lo), "v"(hi)); return r; }
; #define LAS __attribute__((address_space(3)))
; __device__ __forceinline__ float silu_f(float x) { return x * __builtin_amdgcn_rcpf(1.f + __expf(-x)); }
; template <bool NEED_C>
; __device__ __forceinline__ void ssd_stage(LAS unsigned char* lds, const bf16_t* XBC, const float* cw, const float* cb, const float* DT, const float* a_log, int c, int g, int tid, int lane, int wave) {
;     ...
;             for (int i = 0; i < 16; ++i) { float xv[8]; unpack8(raw[3 + i], xv);
;                 float o[8];
; #pragma unroll
;                 for (int e = 0; e < 8; ++e) { o[e] = silu_f(b[e] + w[0][e] * xw[0][e] + w[1][e] * xw[1][e] + w[2][e] * xw[2][e] + w[3][e] * xv[e]); xw[0][e] = xw[1][e]; xw[1][e] = xw[2][e]; xw[2][e] = xv[e]; }
;                 u32x4 pk; pk.x = cvt_pk_bf16(o[0], o[1]); pk.y = cvt_pk_bf16(o[2], o[3]); pk.z = cvt_pk_bf16(o[4], o[5]); pk.w = cvt_pk_bf16(o[6], o[7]);
;                 *(LAS u32x4*)(tile + off_b(seg * 16 + i, tch)) = pk; }
	v_lshlrev_b32_e32 v41, 16, v34
	v_add_f32_e32 v54, v12, v54
	v_add_f32_e32 v72, v54, v55
	v_pk_mov_b32 v[54:55], v[64:65], v[40:41] op_sel:[1,0]
	v_add3_u32 v74, v234, v59, v173
	v_pk_mul_f32 v[56:57], v[152:153], v[54:55]
	v_pk_mul_f32 v[54:55], v[150:151], v[54:55]
	v_add_f32_e32 v56, v58, v56
	v_add_f32_e32 v62, v56, v57
	v_mul_f32_e32 v56, 0xbfb8aa3b, v62
	v_exp_f32_e32 v58, v56
	v_pk_mul_f32 v[56:57], v[152:153], v[40:41]
	v_add_f32_e32 v22, v22, v54
	v_add_f32_e32 v40, v60, v56
	v_add_f32_e32 v40, v40, v57
	v_mul_f32_e32 v56, 0xbfb8aa3b, v40
	v_exp_f32_e32 v56, v56
	v_add_f32_e32 v57, 1.0, v58
	v_rcp_f32_e32 v63, v57
	v_and_b32_e32 v57, 0xffff0000, v34
	v_add_f32_e32 v56, 1.0, v56
	v_rcp_f32_e32 v64, v56
	v_and_b32_e32 v56, 0xffff0000, v30
	v_pk_mov_b32 v[58:59], v[50:51], v[56:57] op_sel:[1,0]
	v_pk_mul_f32 v[50:51], v[14:15], v[50:51]
	v_pk_mul_f32 v[60:61], v[18:19], v[58:59]
	v_add_f32_e32 v50, v23, v50
	v_add_f32_e32 v30, v66, v60
	v_add_f32_e32 v30, v30, v61
	v_mul_f32_e32 v34, 0xbfb8aa3b, v30
	v_exp_f32_e32 v34, v34
	v_add_f32_e32 v60, v50, v51
	v_pk_mul_f32 v[50:51], v[18:19], v[56:57]
	v_mul_f32_e32 v65, v62, v63
	v_add_f32_e32 v50, v60, v50
	v_add_f32_e32 v56, v50, v51
	v_add_f32_e32 v34, 1.0, v34
	v_mul_f32_e32 v50, 0xbfb8aa3b, v56
	v_rcp_f32_e32 v34, v34
	v_exp_f32_e32 v50, v50
	v_lshlrev_b32_e32 v51, 16, v35
	v_mul_f32_e32 v40, v40, v64
	v_mul_f32_e32 v30, v30, v34
	v_add_f32_e32 v34, 1.0, v50
	v_lshlrev_b32_e32 v50, 16, v31
	v_pk_mov_b32 v[60:61], v[48:49], v[50:51] op_sel:[1,0]
	v_pk_mul_f32 v[48:49], v[106:107], v[48:49]
	v_pk_mul_f32 v[62:63], v[110:111], v[60:61]
	v_add_f32_e32 v48, v24, v48
	v_add_f32_e32 v62, v67, v62
	v_add_f32_e32 v62, v62, v63
	v_mul_f32_e32 v63, 0xbfb8aa3b, v62
	v_exp_f32_e32 v63, v63
	v_add_f32_e32 v64, v48, v49
	v_rcp_f32_e32 v34, v34
	v_cvt_pk_bf16_f32 v30, v65, v30
	v_add_f32_e32 v48, 1.0, v63
	v_rcp_f32_e32 v63, v48
	v_pk_mul_f32 v[48:49], v[110:111], v[50:51]
	v_mul_f32_e32 v56, v56, v34
	v_add_f32_e32 v48, v64, v48
	v_add_f32_e32 v50, v48, v49
	v_mul_f32_e32 v48, 0xbfb8aa3b, v50
	v_exp_f32_e32 v48, v48
	v_and_b32_e32 v35, 0xffff0000, v35
	v_mul_f32_e32 v64, v62, v63
	v_pk_mul_f32 v[14:15], v[14:15], v[58:59]
	v_add_f32_e32 v34, 1.0, v48
	v_rcp_f32_e32 v65, v34
	v_and_b32_e32 v34, 0xffff0000, v31
	v_pk_mov_b32 v[48:49], v[46:47], v[34:35] op_sel:[1,0]
	v_pk_mul_f32 v[46:47], v[16:17], v[46:47]
	v_pk_mul_f32 v[62:63], v[20:21], v[48:49]
	v_add_f32_e32 v46, v25, v46
	v_add_f32_e32 v31, v70, v62
	v_add_f32_e32 v31, v31, v63
	v_mul_f32_e32 v62, 0xbfb8aa3b, v31
	v_exp_f32_e32 v62, v62
	v_add_f32_e32 v63, v46, v47
	v_mul_f32_e32 v50, v50, v65
	v_add_f32_e32 v14, v23, v14
	v_add_f32_e32 v46, 1.0, v62
	v_rcp_f32_e32 v62, v46
	v_pk_mul_f32 v[46:47], v[20:21], v[34:35]
	v_add_f32_e32 v23, v14, v15
	v_add_f32_e32 v34, v63, v46
	v_add_f32_e32 v34, v34, v47
	v_mul_f32_e32 v46, 0xbfb8aa3b, v34
	v_exp_f32_e32 v46, v46
	v_mul_f32_e32 v31, v31, v62
	v_cvt_pk_bf16_f32 v31, v64, v31
	v_add_f32_e32 v22, v22, v55
	v_add_f32_e32 v46, 1.0, v46
	v_rcp_f32_e32 v64, v46
	v_pk_mul_f32 v[46:47], v[94:95], v[52:53]
	v_mul_f32_e32 v34, v34, v64
	v_add_f32_e32 v46, v10, v46
	v_add_f32_e32 v65, v46, v47
	v_lshlrev_b32_e32 v46, 16, v32
	v_lshlrev_b32_e32 v47, 16, v36
	v_pk_mov_b32 v[52:53], v[52:53], v[46:47] op_sel:[1,0]
	s_nop 0
	v_pk_mul_f32 v[62:63], v[98:99], v[52:53]
	s_nop 0
	v_add_f32_e32 v62, v71, v62
	v_add_f32_e32 v69, v62, v63
	v_mul_f32_e32 v62, 0xbfb8aa3b, v69
	v_exp_f32_e32 v66, v62
	v_pk_mul_f32 v[62:63], v[98:99], v[46:47]
	s_nop 0
	v_add_f32_e32 v46, v65, v62
	v_add_f32_e32 v46, v46, v63
	v_mul_f32_e32 v62, 0xbfb8aa3b, v46
	v_exp_f32_e32 v62, v62
	v_add_f32_e32 v63, 1.0, v66
	v_rcp_f32_e32 v70, v63
	v_and_b32_e32 v63, 0xffff0000, v36
	v_add_f32_e32 v62, 1.0, v62
	v_rcp_f32_e32 v71, v62
	v_and_b32_e32 v62, 0xffff0000, v32
	v_pk_mov_b32 v[64:65], v[42:43], v[62:63] op_sel:[1,0]
	v_pk_mul_f32 v[42:43], v[2:3], v[42:43]
	v_pk_mul_f32 v[66:67], v[6:7], v[64:65]
	v_add_f32_e32 v42, v11, v42
	v_add_f32_e32 v32, v68, v66
	v_add_f32_e32 v32, v32, v67
	v_mul_f32_e32 v36, 0xbfb8aa3b, v32
	v_exp_f32_e32 v36, v36
	v_add_f32_e32 v66, v42, v43
	v_pk_mul_f32 v[42:43], v[6:7], v[62:63]
	v_mul_f32_e32 v70, v69, v70
	v_add_f32_e32 v42, v66, v42
	v_add_f32_e32 v62, v42, v43
	v_add_f32_e32 v36, 1.0, v36
	v_mul_f32_e32 v42, 0xbfb8aa3b, v62
	v_rcp_f32_e32 v36, v36
	v_exp_f32_e32 v42, v42
	v_lshlrev_b32_e32 v43, 16, v37
	v_mul_f32_e32 v46, v46, v71
	v_mul_f32_e32 v32, v32, v36
	v_add_f32_e32 v36, 1.0, v42
	v_lshlrev_b32_e32 v42, 16, v33
	v_pk_mov_b32 v[66:67], v[38:39], v[42:43] op_sel:[1,0]
	v_pk_mul_f32 v[38:39], v[86:87], v[38:39]
	v_pk_mul_f32 v[68:69], v[90:91], v[66:67]
	v_add_f32_e32 v38, v12, v38
	v_add_f32_e32 v68, v72, v68
	v_add_f32_e32 v68, v68, v69
	v_mul_f32_e32 v69, 0xbfb8aa3b, v68
	v_exp_f32_e32 v69, v69
	v_add_f32_e32 v71, v38, v39
	v_rcp_f32_e32 v36, v36
	v_cvt_pk_bf16_f32 v32, v70, v32
	v_add_f32_e32 v38, 1.0, v69
	v_rcp_f32_e32 v69, v38
	v_pk_mul_f32 v[38:39], v[90:91], v[42:43]
	v_mul_f32_e32 v62, v62, v36
	v_add_f32_e32 v38, v71, v38
	v_add_f32_e32 v42, v38, v39
	v_mul_f32_e32 v38, 0xbfb8aa3b, v42
	v_exp_f32_e32 v38, v38
	v_mul_f32_e32 v68, v68, v69
	v_and_b32_e32 v37, 0xffff0000, v37
	v_pk_mul_f32 v[2:3], v[2:3], v[64:65]
	v_add_f32_e32 v36, 1.0, v38
	v_pk_mul_f32 v[38:39], v[4:5], v[44:45]
	v_rcp_f32_e32 v69, v36
	v_add_f32_e32 v36, v13, v38
	v_add_f32_e32 v70, v36, v39
	v_and_b32_e32 v36, 0xffff0000, v33
	v_pk_mov_b32 v[38:39], v[44:45], v[36:37] op_sel:[1,0]
	v_mul_f32_e32 v42, v42, v69
	v_pk_mul_f32 v[44:45], v[8:9], v[38:39]
	s_waitcnt vmcnt(0)
; __device__ __forceinline__ unsigned cvt_pk_bf16(float lo, float hi) { unsigned r; asm volatile("v_cvt_pk_bf16_f32 %0, %1, %2" : "=v"(r) : "v"(lo), "v"(hi)); return r; }
; #define LAS __attribute__((address_space(3)))
; __device__ __forceinline__ float silu_f(float x) { return x * __builtin_amdgcn_rcpf(1.f + __expf(-x)); }
; template <bool NEED_C>
; __device__ __forceinline__ void ssd_stage(LAS unsigned char* lds, const bf16_t* XBC, const float* cw, const float* cb, const float* DT, const float* a_log, int c, int g, int tid, int lane, int wave) {
;     ...
;             for (int i = 0; i < 16; ++i) { float xv[8]; unpack8(raw[3 + i], xv);
;                 float o[8];
; #pragma unroll
;                 for (int e = 0; e < 8; ++e) { o[e] = silu_f(b[e] + w[0][e] * xw[0][e] + w[1][e] * xw[1][e] + w[2][e] * xw[2][e] + w[3][e] * xv[e]); xw[0][e] = xw[1][e]; xw[1][e] = xw[2][e]; xw[2][e] = xv[e]; }
;                 u32x4 pk; pk.x = cvt_pk_bf16(o[0], o[1]); pk.y = cvt_pk_bf16(o[2], o[3]); pk.z = cvt_pk_bf16(o[4], o[5]); pk.w = cvt_pk_bf16(o[6], o[7]);
;                 *(LAS u32x4*)(tile + off_b(seg * 16 + i, tch)) = pk; }
	v_lshlrev_b32_e32 v69, 16, v28
	v_add_f32_e32 v33, v73, v44
	v_add_f32_e32 v33, v33, v45
	v_mul_f32_e32 v44, 0xbfb8aa3b, v33
	v_exp_f32_e32 v71, v44
	v_pk_mul_f32 v[44:45], v[8:9], v[36:37]
	v_add_f32_e32 v2, v11, v2
	v_add_f32_e32 v36, v70, v44
	v_add_f32_e32 v36, v36, v45
	v_mul_f32_e32 v44, 0xbfb8aa3b, v36
	v_exp_f32_e32 v44, v44
	v_add_f32_e32 v45, 1.0, v71
	v_rcp_f32_e32 v45, v45
	v_add_f32_e32 v11, v2, v3
	v_add_f32_e32 v44, 1.0, v44
	v_rcp_f32_e32 v44, v44
	v_mul_f32_e32 v33, v33, v45
	v_cvt_pk_bf16_f32 v33, v68, v33
	ds_write_b128 v74, v[30:33] offset:3328
	v_mul_f32_e32 v33, v36, v44
	v_cvt_pk_bf16_f32 v30, v40, v56
	v_cvt_pk_bf16_f32 v31, v50, v34
	v_xor_b32_e32 v34, 0xb0, v116
	v_cvt_pk_bf16_f32 v32, v46, v62
	v_cvt_pk_bf16_f32 v33, v42, v33
	v_add3_u32 v34, v234, v34, v173
	ds_write_b128 v34, v[30:33] offset:3584
	v_and_b32_e32 v33, 0xffff0000, v26
	v_mov_b32_e32 v32, v57
	v_pk_mul_f32 v[14:15], v[18:19], v[32:33]
	v_lshlrev_b32_e32 v45, 16, v27
	v_add_f32_e32 v14, v23, v14
	v_add_f32_e32 v18, v14, v15
	v_mul_f32_e32 v14, 0xbfb8aa3b, v18
	v_exp_f32_e32 v19, v14
	v_pk_mul_f32 v[14:15], v[106:107], v[60:61]
	v_mov_b32_e32 v44, v51
	v_add_f32_e32 v14, v24, v14
	v_lshlrev_b32_e32 v31, 16, v26
	v_mov_b32_e32 v30, v41
	v_add_f32_e32 v23, v14, v15
	v_pk_mul_f32 v[14:15], v[110:111], v[44:45]
	v_pk_mul_f32 v[30:31], v[152:153], v[30:31]
	v_add_f32_e32 v14, v23, v14
	v_add_f32_e32 v22, v22, v30
	v_add_f32_e32 v23, v14, v15
	v_add_f32_e32 v22, v22, v31
	v_mul_f32_e32 v14, 0xbfb8aa3b, v23
	v_mul_f32_e32 v26, 0xbfb8aa3b, v22
	v_exp_f32_e32 v14, v14
	v_exp_f32_e32 v26, v26
	v_add_f32_e32 v15, 1.0, v19
	v_and_b32_e32 v31, 0xffff0000, v28
	v_add_f32_e32 v14, 1.0, v14
	v_add_f32_e32 v26, 1.0, v26
	v_rcp_f32_e32 v19, v15
	v_rcp_f32_e32 v28, v14
	v_pk_mul_f32 v[14:15], v[16:17], v[48:49]
	v_and_b32_e32 v27, 0xffff0000, v27
	v_rcp_f32_e32 v24, v26
	v_add_f32_e32 v14, v25, v14
	v_mov_b32_e32 v26, v35
	v_add_f32_e32 v16, v14, v15
	v_pk_mul_f32 v[14:15], v[20:21], v[26:27]
	v_mov_b32_e32 v68, v47
	v_add_f32_e32 v14, v16, v14
	v_add_f32_e32 v16, v14, v15
	v_mul_f32_e32 v14, 0xbfb8aa3b, v16
	v_exp_f32_e32 v14, v14
	v_mov_b32_e32 v30, v63
	v_pk_mul_f32 v[2:3], v[6:7], v[30:31]
	v_lshlrev_b32_e32 v41, 16, v29
	v_add_f32_e32 v14, 1.0, v14
	v_rcp_f32_e32 v20, v14
	v_pk_mul_f32 v[14:15], v[94:95], v[52:53]
	v_add_f32_e32 v2, v11, v2
	v_add_f32_e32 v10, v10, v14
	v_add_f32_e32 v10, v10, v15
	v_pk_mul_f32 v[14:15], v[98:99], v[68:69]
	v_add_f32_e32 v6, v2, v3
	v_add_f32_e32 v10, v10, v14
	v_add_f32_e32 v10, v10, v15
	v_mul_f32_e32 v14, 0xbfb8aa3b, v10
	v_exp_f32_e32 v14, v14
	v_mul_f32_e32 v2, 0xbfb8aa3b, v6
	v_exp_f32_e32 v2, v2
	v_mov_b32_e32 v40, v43
	v_add_f32_e32 v3, 1.0, v14
	v_rcp_f32_e32 v11, v3
	v_add_f32_e32 v14, 1.0, v2
	v_pk_mul_f32 v[2:3], v[86:87], v[66:67]
	v_and_b32_e32 v29, 0xffff0000, v29
	v_add_f32_e32 v2, v12, v2
	v_add_f32_e32 v12, v2, v3
	v_pk_mul_f32 v[2:3], v[90:91], v[40:41]
	v_mul_f32_e32 v18, v18, v19
	v_add_f32_e32 v2, v12, v2
	v_add_f32_e32 v12, v2, v3
	v_mul_f32_e32 v2, 0xbfb8aa3b, v12
	v_exp_f32_e32 v15, v2
	v_pk_mul_f32 v[2:3], v[4:5], v[38:39]
	v_mul_f32_e32 v19, v23, v28
	v_add_f32_e32 v2, v13, v2
	v_mov_b32_e32 v28, v37
	v_add_f32_e32 v4, v2, v3
	v_pk_mul_f32 v[2:3], v[8:9], v[28:29]
	v_add_f32_e32 v5, 1.0, v15
	v_add_f32_e32 v2, v4, v2
	v_add_f32_e32 v2, v2, v3
	v_mul_f32_e32 v3, 0xbfb8aa3b, v2
	v_exp_f32_e32 v3, v3
	v_rcp_f32_e32 v4, v14
	v_rcp_f32_e32 v5, v5
	v_mul_f32_e32 v17, v22, v24
	v_add_f32_e32 v3, 1.0, v3
	v_rcp_f32_e32 v3, v3
	v_mul_f32_e32 v4, v6, v4
	v_mul_f32_e32 v5, v12, v5
	v_mul_f32_e32 v7, v16, v20
	v_mul_f32_e32 v6, v2, v3
	v_mul_f32_e32 v8, v10, v11
	v_cvt_pk_bf16_f32 v2, v17, v18
	v_cvt_pk_bf16_f32 v3, v19, v7
	v_cvt_pk_bf16_f32 v4, v8, v4
	v_cvt_pk_bf16_f32 v5, v5, v6
	v_xor_b32_e32 v6, 0xf0, v116
	v_add3_u32 v6, v234, v6, v174
	ds_write_b128 v6, v[2:5]
	v_mov_b32_e32 v2, s90
